# first counted wait of each tile relaxed by the epilogue's store count so it no longer waits for the previous tile's store acks
# speedup vs baseline: 1.0089x; 1.0089x over previous
.LBB0_1008:
	s_add_i32 s37, s37, 1
	s_lshl_b32 s7, s37, 5
	s_add_i32 s7, s7, s3
	s_ashr_i32 s19, s7, 2
	s_cmp_lt_i32 s19, 16
	s_mov_b64 s[24:25], s[8:9]
	s_cselect_b64 s[8:9], -1, 0
	s_cmp_lt_i32 s7, 64
	s_mov_b64 s[22:23], s[10:11]
	s_cselect_b64 s[10:11], -1, 0
	s_and_b64 s[20:21], s[10:11], exec
	s_mov_b32 s46, s18
	s_cselect_b32 s18, s31, s18
	s_mov_b32 s45, s6
	s_cselect_b32 s6, s19, s6
	s_ashr_i32 s19, s18, 31
	s_and_b64 s[20:21], s[10:11], s[8:9]
	s_lshl_b64 s[8:9], s[18:19], 21
	v_readlane_b32 s0, v250, 46
	v_readlane_b32 s1, v250, 47
	s_add_u32 s10, s0, s8
	s_addc_u32 s11, s1, s9
	s_and_b64 s[8:9], s[20:21], exec
	s_cselect_b32 s19, s11, s23
	s_cselect_b32 s47, s10, s22
	s_ashr_i32 s7, s6, 31
	s_lshl_b64 s[8:9], s[6:7], 21
	v_readlane_b32 s0, v250, 40
	v_readlane_b32 s1, v250, 41
	s_add_u32 s8, s0, s8
	s_addc_u32 s9, s1, s9
	s_and_b64 s[26:27], s[20:21], exec
	s_cselect_b32 s7, s9, s25
	s_cselect_b32 s48, s8, s24
	s_add_u32 s22, s22, 0x100080
	s_addc_u32 s23, s23, 0
	s_add_u32 s49, s24, 0x100
	s_addc_u32 s50, s25, 0
	s_mov_b32 s51, -2
	s_waitcnt lgkmcnt(0)
	ds_read_b128 v[142:145], v155
	ds_read_b128 v[158:161], v155 offset:1024
	ds_read_b128 v[168:171], v155 offset:2048
	ds_read_b128 v[176:179], v155 offset:3072
	ds_read_b128 v[180:183], v156
	ds_read_b128 v[184:187], v156 offset:1024
	ds_read_b128 v[188:191], v156 offset:2048
	ds_read_b128 v[192:195], v156 offset:3072
	s_add_u32 s24, s22, 0xfff00080
	s_addc_u32 s25, s23, -1
	s_cmp_eq_u32 s51, 60
	s_cselect_b32 s27, s19, s25
	s_cselect_b32 s26, s47, s24
	s_cselect_b32 s25, s7, s50
	s_cselect_b32 s24, s48, s49
	s_mov_b32 m0, s40
	ds_read_b128 v[202:205], v157
	ds_read_b128 v[206:209], v157 offset:1024
	ds_read_b128 v[210:213], v157 offset:2048
	ds_read_b128 v[214:217], v157 offset:3072
	ds_read_b128 v[218:221], v157 offset:4096
	ds_read_b128 v[222:225], v157 offset:5120
	ds_read_b128 v[226:229], v157 offset:6144
	ds_read_b128 v[230:233], v157 offset:7168
	global_load_lds_dwordx4 v138, s[22:23]
	s_mov_b32 m0, s41
	s_nop 0
	global_load_lds_dwordx4 v140, s[22:23]
	s_waitcnt vmcnt(24)
	s_waitcnt lgkmcnt(0)
	s_barrier
	v_mfma_f32_16x16x32_bf16 v[126:129], v[142:145], v[202:205], 0
	v_mfma_f32_16x16x32_bf16 v[126:129], v[158:161], v[206:209], v[126:129]
	v_mfma_f32_16x16x32_bf16 v[122:125], v[176:179], v[206:209], 0
	v_mfma_f32_16x16x32_bf16 v[122:125], v[168:171], v[202:205], v[122:125]
	v_mfma_f32_16x16x32_bf16 v[106:109], v[168:171], v[210:213], 0
	v_mfma_f32_16x16x32_bf16 v[106:109], v[176:179], v[214:217], v[106:109]
	v_mfma_f32_16x16x32_bf16 v[110:113], v[158:161], v[214:217], 0
	v_mfma_f32_16x16x32_bf16 v[110:113], v[142:145], v[210:213], v[110:113]
	v_mfma_f32_16x16x32_bf16 v[94:97], v[142:145], v[218:221], 0
	v_mfma_f32_16x16x32_bf16 v[94:97], v[158:161], v[222:225], v[94:97]
	v_mfma_f32_16x16x32_bf16 v[90:93], v[176:179], v[222:225], 0
	v_mfma_f32_16x16x32_bf16 v[90:93], v[168:171], v[218:221], v[90:93]
	v_mfma_f32_16x16x32_bf16 v[74:77], v[168:171], v[226:229], 0
	v_mfma_f32_16x16x32_bf16 v[74:77], v[176:179], v[230:233], v[74:77]
	v_mfma_f32_16x16x32_bf16 v[78:81], v[158:161], v[230:233], 0
	v_mfma_f32_16x16x32_bf16 v[78:81], v[142:145], v[226:229], v[78:81]
	v_mfma_f32_16x16x32_bf16 v[70:73], v[180:183], v[226:229], 0
	v_mfma_f32_16x16x32_bf16 v[70:73], v[184:187], v[230:233], v[70:73]
	v_mfma_f32_16x16x32_bf16 v[66:69], v[192:195], v[230:233], 0
	v_mfma_f32_16x16x32_bf16 v[66:69], v[188:191], v[226:229], v[66:69]
	v_mfma_f32_16x16x32_bf16 v[82:85], v[188:191], v[218:221], 0
	v_mfma_f32_16x16x32_bf16 v[82:85], v[192:195], v[222:225], v[82:85]
	v_mfma_f32_16x16x32_bf16 v[86:89], v[184:187], v[222:225], 0
	v_mfma_f32_16x16x32_bf16 v[86:89], v[180:183], v[218:221], v[86:89]
	v_mfma_f32_16x16x32_bf16 v[102:105], v[180:183], v[210:213], 0
	v_mfma_f32_16x16x32_bf16 v[102:105], v[184:187], v[214:217], v[102:105]
	v_mfma_f32_16x16x32_bf16 v[98:101], v[192:195], v[214:217], 0
	v_mfma_f32_16x16x32_bf16 v[98:101], v[188:191], v[210:213], v[98:101]
	v_mfma_f32_16x16x32_bf16 v[114:117], v[188:191], v[202:205], 0
	v_mfma_f32_16x16x32_bf16 v[114:117], v[192:195], v[206:209], v[114:117]
	v_mfma_f32_16x16x32_bf16 v[118:121], v[184:187], v[206:209], 0
	v_mfma_f32_16x16x32_bf16 v[118:121], v[180:183], v[202:205], v[118:121]
	s_barrier
	s_mov_b32 m0, s42
	s_add_u32 s52, s24, 0x100000
	ds_read_b128 v[202:205], v157 offset:16384
	ds_read_b128 v[206:209], v157 offset:17408
	ds_read_b128 v[210:213], v157 offset:18432
	ds_read_b128 v[214:217], v157 offset:19456
	ds_read_b128 v[218:221], v157 offset:20480
	ds_read_b128 v[222:225], v157 offset:21504
	ds_read_b128 v[226:229], v157 offset:22528
	ds_read_b128 v[230:233], v157 offset:23552
	global_load_lds_dwordx4 v132, s[24:25]
	s_mov_b32 m0, s43
	s_addc_u32 s53, s25, 0
	global_load_lds_dwordx4 v136, s[24:25]
	s_mov_b32 m0, s44
	s_nop 0
	global_load_lds_dwordx4 v132, s[52:53]
	s_add_i32 m0, s44, 0x2000
	s_nop 0
	global_load_lds_dwordx4 v136, s[52:53]
	s_mov_b32 m0, s33
	s_nop 0
	global_load_lds_dwordx4 v130, s[26:27]
	s_mov_b32 m0, s34
	s_nop 0
	global_load_lds_dwordx4 v134, s[26:27]
	s_waitcnt vmcnt(8)
	s_waitcnt lgkmcnt(0)
	s_barrier
	v_mfma_f32_16x16x32_bf16 v[62:65], v[142:145], v[202:205], 0
	v_mfma_f32_16x16x32_bf16 v[62:65], v[158:161], v[206:209], v[62:65]
	v_mfma_f32_16x16x32_bf16 v[58:61], v[176:179], v[206:209], 0
	v_mfma_f32_16x16x32_bf16 v[58:61], v[168:171], v[202:205], v[58:61]
	v_mfma_f32_16x16x32_bf16 v[42:45], v[168:171], v[210:213], 0
	v_mfma_f32_16x16x32_bf16 v[42:45], v[176:179], v[214:217], v[42:45]
	v_mfma_f32_16x16x32_bf16 v[46:49], v[158:161], v[214:217], 0
	v_mfma_f32_16x16x32_bf16 v[46:49], v[142:145], v[210:213], v[46:49]
	v_mfma_f32_16x16x32_bf16 v[30:33], v[142:145], v[218:221], 0
	v_mfma_f32_16x16x32_bf16 v[30:33], v[158:161], v[222:225], v[30:33]
	v_mfma_f32_16x16x32_bf16 v[26:29], v[176:179], v[222:225], 0
	v_mfma_f32_16x16x32_bf16 v[26:29], v[168:171], v[218:221], v[26:29]
	v_mfma_f32_16x16x32_bf16 v[10:13], v[168:171], v[226:229], 0
	v_mfma_f32_16x16x32_bf16 v[10:13], v[176:179], v[230:233], v[10:13]
	v_mfma_f32_16x16x32_bf16 v[14:17], v[158:161], v[230:233], 0
	v_mfma_f32_16x16x32_bf16 v[14:17], v[142:145], v[226:229], v[14:17]
	v_mfma_f32_16x16x32_bf16 v[6:9], v[180:183], v[226:229], 0
	v_mfma_f32_16x16x32_bf16 v[6:9], v[184:187], v[230:233], v[6:9]
	v_mfma_f32_16x16x32_bf16 v[2:5], v[192:195], v[230:233], 0
	v_mfma_f32_16x16x32_bf16 v[2:5], v[188:191], v[226:229], v[2:5]
	v_mfma_f32_16x16x32_bf16 v[18:21], v[188:191], v[218:221], 0
	v_mfma_f32_16x16x32_bf16 v[18:21], v[192:195], v[222:225], v[18:21]
	v_mfma_f32_16x16x32_bf16 v[22:25], v[184:187], v[222:225], 0
	v_mfma_f32_16x16x32_bf16 v[22:25], v[180:183], v[218:221], v[22:25]
	v_mfma_f32_16x16x32_bf16 v[38:41], v[180:183], v[210:213], 0
	v_mfma_f32_16x16x32_bf16 v[38:41], v[184:187], v[214:217], v[38:41]
	v_mfma_f32_16x16x32_bf16 v[34:37], v[192:195], v[214:217], 0
	v_mfma_f32_16x16x32_bf16 v[34:37], v[188:191], v[210:213], v[34:37]
	v_mfma_f32_16x16x32_bf16 v[50:53], v[188:191], v[202:205], 0
	v_mfma_f32_16x16x32_bf16 v[50:53], v[192:195], v[206:209], v[50:53]
	v_mfma_f32_16x16x32_bf16 v[54:57], v[184:187], v[206:209], 0
	v_mfma_f32_16x16x32_bf16 v[54:57], v[180:183], v[202:205], v[54:57]
	s_barrier
	s_add_i32 s52, 0, 0x18000
	v_add_u32_e32 v166, s52, v153
	s_add_i32 s53, 0, 0x1c000
	ds_read_b128 v[142:145], v166
	ds_read_b128 v[158:161], v166 offset:1024
	ds_read_b128 v[168:171], v166 offset:2048
	ds_read_b128 v[176:179], v166 offset:3072
	v_add_u32_e32 v166, s53, v153
	ds_read_b128 v[180:183], v166
	ds_read_b128 v[184:187], v166 offset:1024
	ds_read_b128 v[188:191], v166 offset:2048
	ds_read_b128 v[192:195], v166 offset:3072
	s_add_u32 s26, s26, 0x100000
	s_addc_u32 s27, s27, 0
	s_mov_b32 m0, s35
	ds_read_b128 v[202:205], v157 offset:32768
	ds_read_b128 v[206:209], v157 offset:33792
	ds_read_b128 v[210:213], v157 offset:34816
	ds_read_b128 v[214:217], v157 offset:35840
	ds_read_b128 v[218:221], v157 offset:36864
	ds_read_b128 v[222:225], v157 offset:37888
	ds_read_b128 v[226:229], v157 offset:38912
	ds_read_b128 v[230:233], v157 offset:39936
	global_load_lds_dwordx4 v130, s[26:27]
	s_mov_b32 m0, s36
	s_nop 0
	global_load_lds_dwordx4 v134, s[26:27]
	s_waitcnt vmcnt(8)
	s_waitcnt lgkmcnt(0)
	s_barrier
	v_mfma_f32_16x16x32_bf16 v[126:129], v[142:145], v[202:205], v[126:129]
	v_mfma_f32_16x16x32_bf16 v[126:129], v[158:161], v[206:209], v[126:129]
	v_mfma_f32_16x16x32_bf16 v[122:125], v[176:179], v[206:209], v[122:125]
	v_mfma_f32_16x16x32_bf16 v[122:125], v[168:171], v[202:205], v[122:125]
	v_mfma_f32_16x16x32_bf16 v[106:109], v[168:171], v[210:213], v[106:109]
	v_mfma_f32_16x16x32_bf16 v[106:109], v[176:179], v[214:217], v[106:109]
	v_mfma_f32_16x16x32_bf16 v[110:113], v[158:161], v[214:217], v[110:113]
	v_mfma_f32_16x16x32_bf16 v[110:113], v[142:145], v[210:213], v[110:113]
	v_mfma_f32_16x16x32_bf16 v[94:97], v[142:145], v[218:221], v[94:97]
	v_mfma_f32_16x16x32_bf16 v[94:97], v[158:161], v[222:225], v[94:97]
	v_mfma_f32_16x16x32_bf16 v[90:93], v[176:179], v[222:225], v[90:93]
	v_mfma_f32_16x16x32_bf16 v[90:93], v[168:171], v[218:221], v[90:93]
	v_mfma_f32_16x16x32_bf16 v[74:77], v[168:171], v[226:229], v[74:77]
	v_mfma_f32_16x16x32_bf16 v[74:77], v[176:179], v[230:233], v[74:77]
	v_mfma_f32_16x16x32_bf16 v[78:81], v[158:161], v[230:233], v[78:81]
	v_mfma_f32_16x16x32_bf16 v[78:81], v[142:145], v[226:229], v[78:81]
	v_mfma_f32_16x16x32_bf16 v[70:73], v[180:183], v[226:229], v[70:73]
	v_mfma_f32_16x16x32_bf16 v[70:73], v[184:187], v[230:233], v[70:73]
	v_mfma_f32_16x16x32_bf16 v[66:69], v[192:195], v[230:233], v[66:69]
	v_mfma_f32_16x16x32_bf16 v[66:69], v[188:191], v[226:229], v[66:69]
	v_mfma_f32_16x16x32_bf16 v[82:85], v[188:191], v[218:221], v[82:85]
	v_mfma_f32_16x16x32_bf16 v[82:85], v[192:195], v[222:225], v[82:85]
	v_mfma_f32_16x16x32_bf16 v[86:89], v[184:187], v[222:225], v[86:89]
	v_mfma_f32_16x16x32_bf16 v[86:89], v[180:183], v[218:221], v[86:89]
	v_mfma_f32_16x16x32_bf16 v[102:105], v[180:183], v[210:213], v[102:105]
	v_mfma_f32_16x16x32_bf16 v[102:105], v[184:187], v[214:217], v[102:105]
	v_mfma_f32_16x16x32_bf16 v[98:101], v[192:195], v[214:217], v[98:101]
	v_mfma_f32_16x16x32_bf16 v[98:101], v[188:191], v[210:213], v[98:101]
	v_mfma_f32_16x16x32_bf16 v[114:117], v[188:191], v[202:205], v[114:117]
	v_mfma_f32_16x16x32_bf16 v[114:117], v[192:195], v[206:209], v[114:117]
	v_mfma_f32_16x16x32_bf16 v[118:121], v[184:187], v[206:209], v[118:121]
	v_mfma_f32_16x16x32_bf16 v[118:121], v[180:183], v[202:205], v[118:121]
	s_barrier
	s_add_u32 s98, s26, 0xfff00080
	s_addc_u32 s99, s27, -1
	s_add_u32 s24, s24, 0x80
	s_addc_u32 s25, s25, 0
	s_add_i32 s26, s52, s30
	s_mov_b32 m0, s26
	ds_read_b128 v[202:205], v157 offset:49152
	ds_read_b128 v[206:209], v157 offset:50176
	ds_read_b128 v[210:213], v157 offset:51200
	ds_read_b128 v[214:217], v157 offset:52224
	ds_read_b128 v[218:221], v157 offset:53248
	ds_read_b128 v[222:225], v157 offset:54272
	ds_read_b128 v[226:229], v157 offset:55296
	ds_read_b128 v[230:233], v157 offset:56320
	global_load_lds_dwordx4 v132, s[24:25]
	s_add_i32 m0, s26, 0x2000
	s_add_i32 s26, s53, s30
	global_load_lds_dwordx4 v136, s[24:25]
	s_add_u32 s24, s24, 0x100000
	s_addc_u32 s25, s25, 0
	s_mov_b32 m0, s26
	s_nop 0
	global_load_lds_dwordx4 v132, s[24:25]
	s_add_i32 m0, s26, 0x2000
	s_nop 0
	global_load_lds_dwordx4 v136, s[24:25]
	s_mov_b32 m0, s38
	s_nop 0
	global_load_lds_dwordx4 v130, s[98:99]
	s_mov_b32 m0, s39
	s_nop 0
	global_load_lds_dwordx4 v134, s[98:99]
	s_waitcnt vmcnt(8)
	s_waitcnt lgkmcnt(0)
	s_barrier
	v_mfma_f32_16x16x32_bf16 v[62:65], v[142:145], v[202:205], v[62:65]
	v_mfma_f32_16x16x32_bf16 v[62:65], v[158:161], v[206:209], v[62:65]
	v_mfma_f32_16x16x32_bf16 v[58:61], v[176:179], v[206:209], v[58:61]
	v_mfma_f32_16x16x32_bf16 v[58:61], v[168:171], v[202:205], v[58:61]
	v_mfma_f32_16x16x32_bf16 v[42:45], v[168:171], v[210:213], v[42:45]
	v_mfma_f32_16x16x32_bf16 v[42:45], v[176:179], v[214:217], v[42:45]
	v_mfma_f32_16x16x32_bf16 v[46:49], v[158:161], v[214:217], v[46:49]
	v_mfma_f32_16x16x32_bf16 v[46:49], v[142:145], v[210:213], v[46:49]
	v_mfma_f32_16x16x32_bf16 v[30:33], v[142:145], v[218:221], v[30:33]
	v_mfma_f32_16x16x32_bf16 v[30:33], v[158:161], v[222:225], v[30:33]
	v_mfma_f32_16x16x32_bf16 v[26:29], v[176:179], v[222:225], v[26:29]
	v_mfma_f32_16x16x32_bf16 v[26:29], v[168:171], v[218:221], v[26:29]
	v_mfma_f32_16x16x32_bf16 v[10:13], v[168:171], v[226:229], v[10:13]
	v_mfma_f32_16x16x32_bf16 v[10:13], v[176:179], v[230:233], v[10:13]
	v_mfma_f32_16x16x32_bf16 v[14:17], v[158:161], v[230:233], v[14:17]
	v_mfma_f32_16x16x32_bf16 v[14:17], v[142:145], v[226:229], v[14:17]
	v_mfma_f32_16x16x32_bf16 v[6:9], v[180:183], v[226:229], v[6:9]
	v_mfma_f32_16x16x32_bf16 v[6:9], v[184:187], v[230:233], v[6:9]
	v_mfma_f32_16x16x32_bf16 v[2:5], v[192:195], v[230:233], v[2:5]
	v_mfma_f32_16x16x32_bf16 v[2:5], v[188:191], v[226:229], v[2:5]
	v_mfma_f32_16x16x32_bf16 v[18:21], v[188:191], v[218:221], v[18:21]
	v_mfma_f32_16x16x32_bf16 v[18:21], v[192:195], v[222:225], v[18:21]
	v_mfma_f32_16x16x32_bf16 v[22:25], v[184:187], v[222:225], v[22:25]
	v_mfma_f32_16x16x32_bf16 v[22:25], v[180:183], v[218:221], v[22:25]
	v_mfma_f32_16x16x32_bf16 v[38:41], v[180:183], v[210:213], v[38:41]
	v_mfma_f32_16x16x32_bf16 v[38:41], v[184:187], v[214:217], v[38:41]
	v_mfma_f32_16x16x32_bf16 v[34:37], v[192:195], v[214:217], v[34:37]
	v_mfma_f32_16x16x32_bf16 v[34:37], v[188:191], v[210:213], v[34:37]
	v_mfma_f32_16x16x32_bf16 v[50:53], v[188:191], v[202:205], v[50:53]
	v_mfma_f32_16x16x32_bf16 v[50:53], v[192:195], v[206:209], v[50:53]
	v_mfma_f32_16x16x32_bf16 v[54:57], v[184:187], v[206:209], v[54:57]
	v_mfma_f32_16x16x32_bf16 v[54:57], v[180:183], v[202:205], v[54:57]
	s_barrier
	s_add_i32 s51, s51, 2
	s_add_u32 s22, s22, 0x100
	s_addc_u32 s23, s23, 0
	s_add_u32 s49, s49, 0x100
	s_addc_u32 s50, s50, 0

.LBB0_1171:
	s_add_i32 s36, s36, 1
	s_mov_b32 s52, s6
	s_lshl_b32 s6, s36, 5
	s_add_i32 s6, s6, s3
	s_mov_b64 s[22:23], s[8:9]
	s_lshl_b32 s8, s6, 3
	s_ashr_i32 s7, s6, 2
	s_add_i32 s8, s8, s39
	s_cmpk_lt_i32 s6, 0x158
	s_cselect_b32 s6, s7, s8
	s_mov_b32 s53, s26
	s_cselect_b32 s26, s40, 32
	s_cmpk_lt_i32 s6, 0x56
	s_cselect_b64 s[18:19], -1, 0
	s_lshl_b32 s7, s26, 21
	v_readlane_b32 s0, v250, 46
	s_mov_b64 s[20:21], s[10:11]
	v_readlane_b32 s1, v250, 47
	s_add_u32 s10, s0, s7
	s_addc_u32 s11, s1, 0
	s_and_b64 s[8:9], s[18:19], exec
	s_cselect_b32 s54, s11, s21
	s_cselect_b32 s55, s10, s20
	s_ashr_i32 s7, s6, 31
	s_lshl_b64 s[8:9], s[6:7], 21
	s_add_u32 s8, s27, s8
	s_addc_u32 s9, s30, s9
	s_and_b64 s[24:25], s[18:19], exec
	s_cselect_b32 s7, s9, s23
	s_cselect_b32 s56, s8, s22
	s_add_u32 s20, s20, 0x100080
	s_addc_u32 s21, s21, 0
	s_add_u32 s57, s22, 0x100
	s_addc_u32 s60, s23, 0
	s_mov_b32 s61, -2
	s_waitcnt lgkmcnt(0)
	s_add_u32 s62, s20, 0xfff00000
	s_addc_u32 s63, s21, -1
	s_mov_b32 m0, s37
	ds_read_b128 v[142:145], v148
	global_load_lds_dwordx4 v130, s[62:63]
	s_mov_b32 m0, s38
	ds_read_b128 v[154:157], v148 offset:1024
	global_load_lds_dwordx4 v134, s[62:63]
	s_mov_b32 m0, s42
	ds_read_b128 v[158:161], v148 offset:2048
	global_load_lds_dwordx4 v138, s[20:21]
	s_mov_b32 m0, s43
	ds_read_b128 v[168:171], v148 offset:3072
	global_load_lds_dwordx4 v140, s[20:21]
	ds_read_b128 v[176:179], v149
	ds_read_b128 v[180:183], v149 offset:1024
	ds_read_b128 v[184:187], v149 offset:2048
	ds_read_b128 v[188:191], v149 offset:3072
	s_add_u32 s22, s20, 0xfff00080
	s_addc_u32 s23, s21, -1
	s_cmp_eq_u32 s61, 60
	s_cselect_b32 s25, s54, s23
	s_cselect_b32 s24, s55, s22
	s_cselect_b32 s23, s7, s60
	s_cselect_b32 s22, s56, s57
	ds_read_b128 v[192:195], v150
	ds_read_b128 v[202:205], v150 offset:1024
	ds_read_b128 v[206:209], v150 offset:2048
	ds_read_b128 v[210:213], v150 offset:3072
	ds_read_b128 v[214:217], v150 offset:4096
	ds_read_b128 v[218:221], v150 offset:5120
	ds_read_b128 v[222:225], v150 offset:6144
	ds_read_b128 v[226:229], v150 offset:7168
	s_waitcnt vmcnt(16)
	s_waitcnt lgkmcnt(0)
	s_barrier
	v_mfma_f32_16x16x32_bf16 v[126:129], v[142:145], v[192:195], 0
	v_mfma_f32_16x16x32_bf16 v[126:129], v[154:157], v[202:205], v[126:129]
	v_mfma_f32_16x16x32_bf16 v[118:121], v[168:171], v[202:205], 0
	v_mfma_f32_16x16x32_bf16 v[118:121], v[158:161], v[192:195], v[118:121]
	v_mfma_f32_16x16x32_bf16 v[102:105], v[158:161], v[206:209], 0
	v_mfma_f32_16x16x32_bf16 v[102:105], v[168:171], v[210:213], v[102:105]
	v_mfma_f32_16x16x32_bf16 v[110:113], v[154:157], v[210:213], 0
	v_mfma_f32_16x16x32_bf16 v[110:113], v[142:145], v[206:209], v[110:113]
	v_mfma_f32_16x16x32_bf16 v[94:97], v[142:145], v[214:217], 0
	v_mfma_f32_16x16x32_bf16 v[94:97], v[154:157], v[218:221], v[94:97]
	v_mfma_f32_16x16x32_bf16 v[86:89], v[168:171], v[218:221], 0
	v_mfma_f32_16x16x32_bf16 v[86:89], v[158:161], v[214:217], v[86:89]
	v_mfma_f32_16x16x32_bf16 v[70:73], v[158:161], v[222:225], 0
	v_mfma_f32_16x16x32_bf16 v[70:73], v[168:171], v[226:229], v[70:73]
	v_mfma_f32_16x16x32_bf16 v[78:81], v[154:157], v[226:229], 0
	v_mfma_f32_16x16x32_bf16 v[78:81], v[142:145], v[222:225], v[78:81]
	v_mfma_f32_16x16x32_bf16 v[74:77], v[176:179], v[222:225], 0
	v_mfma_f32_16x16x32_bf16 v[74:77], v[180:183], v[226:229], v[74:77]
	v_mfma_f32_16x16x32_bf16 v[66:69], v[188:191], v[226:229], 0
	v_mfma_f32_16x16x32_bf16 v[66:69], v[184:187], v[222:225], v[66:69]
	v_mfma_f32_16x16x32_bf16 v[82:85], v[184:187], v[214:217], 0
	v_mfma_f32_16x16x32_bf16 v[82:85], v[188:191], v[218:221], v[82:85]
	v_mfma_f32_16x16x32_bf16 v[90:93], v[180:183], v[218:221], 0
	v_mfma_f32_16x16x32_bf16 v[90:93], v[176:179], v[214:217], v[90:93]
	v_mfma_f32_16x16x32_bf16 v[106:109], v[176:179], v[206:209], 0
	v_mfma_f32_16x16x32_bf16 v[106:109], v[180:183], v[210:213], v[106:109]
	v_mfma_f32_16x16x32_bf16 v[98:101], v[188:191], v[210:213], 0
	v_mfma_f32_16x16x32_bf16 v[98:101], v[184:187], v[206:209], v[98:101]
	v_mfma_f32_16x16x32_bf16 v[114:117], v[184:187], v[192:195], 0
	v_mfma_f32_16x16x32_bf16 v[114:117], v[188:191], v[202:205], v[114:117]
	v_mfma_f32_16x16x32_bf16 v[122:125], v[180:183], v[202:205], 0
	v_mfma_f32_16x16x32_bf16 v[122:125], v[176:179], v[192:195], v[122:125]
	s_barrier
	s_mov_b32 m0, s44
	s_add_u32 s62, s22, 0x100000
	global_load_lds_dwordx4 v132, s[22:23]
	s_mov_b32 m0, s45
	s_addc_u32 s63, s23, 0
	global_load_lds_dwordx4 v136, s[22:23]
	s_mov_b32 m0, s46
	ds_read_b128 v[192:195], v150 offset:16384
	global_load_lds_dwordx4 v132, s[62:63]
	s_mov_b32 m0, s47
	ds_read_b128 v[202:205], v150 offset:17408
	global_load_lds_dwordx4 v136, s[62:63]
	ds_read_b128 v[206:209], v150 offset:18432
	ds_read_b128 v[210:213], v150 offset:19456
	ds_read_b128 v[214:217], v150 offset:20480
	ds_read_b128 v[218:221], v150 offset:21504
	ds_read_b128 v[222:225], v150 offset:22528
	ds_read_b128 v[226:229], v150 offset:23552
	s_waitcnt vmcnt(6)
	s_waitcnt lgkmcnt(0)
	s_barrier
	v_mfma_f32_16x16x32_bf16 v[62:65], v[142:145], v[192:195], 0
	v_mfma_f32_16x16x32_bf16 v[62:65], v[154:157], v[202:205], v[62:65]
	v_mfma_f32_16x16x32_bf16 v[54:57], v[168:171], v[202:205], 0
	v_mfma_f32_16x16x32_bf16 v[54:57], v[158:161], v[192:195], v[54:57]
	v_mfma_f32_16x16x32_bf16 v[38:41], v[158:161], v[206:209], 0
	v_mfma_f32_16x16x32_bf16 v[38:41], v[168:171], v[210:213], v[38:41]
	v_mfma_f32_16x16x32_bf16 v[46:49], v[154:157], v[210:213], 0
	v_mfma_f32_16x16x32_bf16 v[46:49], v[142:145], v[206:209], v[46:49]
	v_mfma_f32_16x16x32_bf16 v[30:33], v[142:145], v[214:217], 0
	v_mfma_f32_16x16x32_bf16 v[30:33], v[154:157], v[218:221], v[30:33]
	v_mfma_f32_16x16x32_bf16 v[22:25], v[168:171], v[218:221], 0
	v_mfma_f32_16x16x32_bf16 v[22:25], v[158:161], v[214:217], v[22:25]
	v_mfma_f32_16x16x32_bf16 v[6:9], v[158:161], v[222:225], 0
	v_mfma_f32_16x16x32_bf16 v[6:9], v[168:171], v[226:229], v[6:9]
	v_mfma_f32_16x16x32_bf16 v[14:17], v[154:157], v[226:229], 0
	v_mfma_f32_16x16x32_bf16 v[14:17], v[142:145], v[222:225], v[14:17]
	v_mfma_f32_16x16x32_bf16 v[10:13], v[176:179], v[222:225], 0
	v_mfma_f32_16x16x32_bf16 v[10:13], v[180:183], v[226:229], v[10:13]
	v_mfma_f32_16x16x32_bf16 v[2:5], v[188:191], v[226:229], 0
	v_mfma_f32_16x16x32_bf16 v[2:5], v[184:187], v[222:225], v[2:5]
	v_mfma_f32_16x16x32_bf16 v[18:21], v[184:187], v[214:217], 0
	v_mfma_f32_16x16x32_bf16 v[18:21], v[188:191], v[218:221], v[18:21]
	v_mfma_f32_16x16x32_bf16 v[26:29], v[180:183], v[218:221], 0
	v_mfma_f32_16x16x32_bf16 v[26:29], v[176:179], v[214:217], v[26:29]
	v_mfma_f32_16x16x32_bf16 v[42:45], v[176:179], v[206:209], 0
	v_mfma_f32_16x16x32_bf16 v[42:45], v[180:183], v[210:213], v[42:45]
	v_mfma_f32_16x16x32_bf16 v[34:37], v[188:191], v[210:213], 0
	v_mfma_f32_16x16x32_bf16 v[34:37], v[184:187], v[206:209], v[34:37]
	v_mfma_f32_16x16x32_bf16 v[50:53], v[184:187], v[192:195], 0
	v_mfma_f32_16x16x32_bf16 v[50:53], v[188:191], v[202:205], v[50:53]
	v_mfma_f32_16x16x32_bf16 v[58:61], v[180:183], v[202:205], 0
	v_mfma_f32_16x16x32_bf16 v[58:61], v[176:179], v[192:195], v[58:61]
	s_barrier
	s_mov_b32 m0, s31
	ds_read_b128 v[142:145], v151
	global_load_lds_dwordx4 v130, s[24:25]
	s_mov_b32 m0, s33
	ds_read_b128 v[154:157], v151 offset:1024
	global_load_lds_dwordx4 v134, s[24:25]
	s_add_u32 s24, s24, 0x100000
	s_addc_u32 s25, s25, 0
	s_mov_b32 m0, s34
	ds_read_b128 v[158:161], v151 offset:2048
	global_load_lds_dwordx4 v130, s[24:25]
	s_mov_b32 m0, s35
	ds_read_b128 v[168:171], v151 offset:3072
	global_load_lds_dwordx4 v134, s[24:25]
	ds_read_b128 v[176:179], v152
	ds_read_b128 v[180:183], v152 offset:1024
	ds_read_b128 v[184:187], v152 offset:2048
	ds_read_b128 v[188:191], v152 offset:3072
	ds_read_b128 v[192:195], v150 offset:32768
	ds_read_b128 v[202:205], v150 offset:33792
	ds_read_b128 v[206:209], v150 offset:34816
	ds_read_b128 v[210:213], v150 offset:35840
	ds_read_b128 v[214:217], v150 offset:36864
	ds_read_b128 v[218:221], v150 offset:37888
	ds_read_b128 v[222:225], v150 offset:38912
	ds_read_b128 v[226:229], v150 offset:39936
	s_waitcnt vmcnt(8)
	s_waitcnt lgkmcnt(0)
	s_barrier
	v_mfma_f32_16x16x32_bf16 v[126:129], v[142:145], v[192:195], v[126:129]
	v_mfma_f32_16x16x32_bf16 v[126:129], v[154:157], v[202:205], v[126:129]
	v_mfma_f32_16x16x32_bf16 v[118:121], v[168:171], v[202:205], v[118:121]
	v_mfma_f32_16x16x32_bf16 v[118:121], v[158:161], v[192:195], v[118:121]
	v_mfma_f32_16x16x32_bf16 v[102:105], v[158:161], v[206:209], v[102:105]
	v_mfma_f32_16x16x32_bf16 v[102:105], v[168:171], v[210:213], v[102:105]
	v_mfma_f32_16x16x32_bf16 v[110:113], v[154:157], v[210:213], v[110:113]
	v_mfma_f32_16x16x32_bf16 v[110:113], v[142:145], v[206:209], v[110:113]
	v_mfma_f32_16x16x32_bf16 v[94:97], v[142:145], v[214:217], v[94:97]
	v_mfma_f32_16x16x32_bf16 v[94:97], v[154:157], v[218:221], v[94:97]
	v_mfma_f32_16x16x32_bf16 v[86:89], v[168:171], v[218:221], v[86:89]
	v_mfma_f32_16x16x32_bf16 v[86:89], v[158:161], v[214:217], v[86:89]
	v_mfma_f32_16x16x32_bf16 v[70:73], v[158:161], v[222:225], v[70:73]
	v_mfma_f32_16x16x32_bf16 v[70:73], v[168:171], v[226:229], v[70:73]
	v_mfma_f32_16x16x32_bf16 v[78:81], v[154:157], v[226:229], v[78:81]
	v_mfma_f32_16x16x32_bf16 v[78:81], v[142:145], v[222:225], v[78:81]
	v_mfma_f32_16x16x32_bf16 v[74:77], v[176:179], v[222:225], v[74:77]
	v_mfma_f32_16x16x32_bf16 v[74:77], v[180:183], v[226:229], v[74:77]
	v_mfma_f32_16x16x32_bf16 v[66:69], v[188:191], v[226:229], v[66:69]
	v_mfma_f32_16x16x32_bf16 v[66:69], v[184:187], v[222:225], v[66:69]
	v_mfma_f32_16x16x32_bf16 v[82:85], v[184:187], v[214:217], v[82:85]
	v_mfma_f32_16x16x32_bf16 v[82:85], v[188:191], v[218:221], v[82:85]
	v_mfma_f32_16x16x32_bf16 v[90:93], v[180:183], v[218:221], v[90:93]
	v_mfma_f32_16x16x32_bf16 v[90:93], v[176:179], v[214:217], v[90:93]
	v_mfma_f32_16x16x32_bf16 v[106:109], v[176:179], v[206:209], v[106:109]
	v_mfma_f32_16x16x32_bf16 v[106:109], v[180:183], v[210:213], v[106:109]
	v_mfma_f32_16x16x32_bf16 v[98:101], v[188:191], v[210:213], v[98:101]
	v_mfma_f32_16x16x32_bf16 v[98:101], v[184:187], v[206:209], v[98:101]
	v_mfma_f32_16x16x32_bf16 v[114:117], v[184:187], v[192:195], v[114:117]
	v_mfma_f32_16x16x32_bf16 v[114:117], v[188:191], v[202:205], v[114:117]
	v_mfma_f32_16x16x32_bf16 v[122:125], v[180:183], v[202:205], v[122:125]
	v_mfma_f32_16x16x32_bf16 v[122:125], v[176:179], v[192:195], v[122:125]
	s_barrier
	s_mov_b32 m0, s48
	s_add_u32 s22, s22, 0x80
	s_addc_u32 s23, s23, 0
	global_load_lds_dwordx4 v132, s[22:23]
	s_mov_b32 m0, s49
	ds_read_b128 v[192:195], v150 offset:49152
	global_load_lds_dwordx4 v136, s[22:23]
	s_mov_b32 m0, s50
	s_add_u32 s22, s22, 0x100000
	s_addc_u32 s23, s23, 0
	global_load_lds_dwordx4 v132, s[22:23]
	s_mov_b32 m0, s51
	ds_read_b128 v[202:205], v150 offset:50176
	global_load_lds_dwordx4 v136, s[22:23]
	ds_read_b128 v[206:209], v150 offset:51200
	ds_read_b128 v[210:213], v150 offset:52224
	ds_read_b128 v[214:217], v150 offset:53248
	ds_read_b128 v[218:221], v150 offset:54272
	ds_read_b128 v[222:225], v150 offset:55296
	ds_read_b128 v[226:229], v150 offset:56320
	s_waitcnt vmcnt(6)
	s_waitcnt lgkmcnt(0)
	s_barrier
	v_mfma_f32_16x16x32_bf16 v[62:65], v[142:145], v[192:195], v[62:65]
	v_mfma_f32_16x16x32_bf16 v[62:65], v[154:157], v[202:205], v[62:65]
	v_mfma_f32_16x16x32_bf16 v[54:57], v[168:171], v[202:205], v[54:57]
	v_mfma_f32_16x16x32_bf16 v[54:57], v[158:161], v[192:195], v[54:57]
	v_mfma_f32_16x16x32_bf16 v[38:41], v[158:161], v[206:209], v[38:41]
	v_mfma_f32_16x16x32_bf16 v[38:41], v[168:171], v[210:213], v[38:41]
	v_mfma_f32_16x16x32_bf16 v[46:49], v[154:157], v[210:213], v[46:49]
	v_mfma_f32_16x16x32_bf16 v[46:49], v[142:145], v[206:209], v[46:49]
	v_mfma_f32_16x16x32_bf16 v[30:33], v[142:145], v[214:217], v[30:33]
	v_mfma_f32_16x16x32_bf16 v[30:33], v[154:157], v[218:221], v[30:33]
	v_mfma_f32_16x16x32_bf16 v[22:25], v[168:171], v[218:221], v[22:25]
	v_mfma_f32_16x16x32_bf16 v[22:25], v[158:161], v[214:217], v[22:25]
	v_mfma_f32_16x16x32_bf16 v[6:9], v[158:161], v[222:225], v[6:9]
	v_mfma_f32_16x16x32_bf16 v[6:9], v[168:171], v[226:229], v[6:9]
	v_mfma_f32_16x16x32_bf16 v[14:17], v[154:157], v[226:229], v[14:17]
	v_mfma_f32_16x16x32_bf16 v[14:17], v[142:145], v[222:225], v[14:17]
	v_mfma_f32_16x16x32_bf16 v[10:13], v[176:179], v[222:225], v[10:13]
	v_mfma_f32_16x16x32_bf16 v[10:13], v[180:183], v[226:229], v[10:13]
	v_mfma_f32_16x16x32_bf16 v[2:5], v[188:191], v[226:229], v[2:5]
	v_mfma_f32_16x16x32_bf16 v[2:5], v[184:187], v[222:225], v[2:5]
	v_mfma_f32_16x16x32_bf16 v[18:21], v[184:187], v[214:217], v[18:21]
	v_mfma_f32_16x16x32_bf16 v[18:21], v[188:191], v[218:221], v[18:21]
	v_mfma_f32_16x16x32_bf16 v[26:29], v[180:183], v[218:221], v[26:29]
	v_mfma_f32_16x16x32_bf16 v[26:29], v[176:179], v[214:217], v[26:29]
	v_mfma_f32_16x16x32_bf16 v[42:45], v[176:179], v[206:209], v[42:45]
	v_mfma_f32_16x16x32_bf16 v[42:45], v[180:183], v[210:213], v[42:45]
	v_mfma_f32_16x16x32_bf16 v[34:37], v[188:191], v[210:213], v[34:37]
	v_mfma_f32_16x16x32_bf16 v[34:37], v[184:187], v[206:209], v[34:37]
	v_mfma_f32_16x16x32_bf16 v[50:53], v[184:187], v[192:195], v[50:53]
	v_mfma_f32_16x16x32_bf16 v[50:53], v[188:191], v[202:205], v[50:53]
	v_mfma_f32_16x16x32_bf16 v[58:61], v[180:183], v[202:205], v[58:61]
	v_mfma_f32_16x16x32_bf16 v[58:61], v[176:179], v[192:195], v[58:61]
	s_barrier
	s_add_i32 s61, s61, 2
	s_add_u32 s20, s20, 0x100
	s_addc_u32 s21, s21, 0
	s_add_u32 s57, s57, 0x100
	s_addc_u32 s60, s60, 0

.LBB0_1417:
	s_and_b64 s[18:19], s[18:19], exec
	s_cselect_b32 s19, s9, s23
	s_cselect_b32 s18, s8, s22
	s_add_u32 s22, s22, 0x2b0080
	s_addc_u32 s23, s23, 0
	s_add_u32 s53, s24, 0x100
	s_addc_u32 s54, s25, 0
	s_mov_b32 s55, -2
	s_waitcnt lgkmcnt(0)
	s_add_u32 s56, s22, 0xffd50000
	s_addc_u32 s57, s23, -1
	s_mov_b32 m0, s40
	ds_read_b128 v[142:145], v156
	global_load_lds_dwordx4 v130, s[56:57]
	s_mov_b32 m0, s41
	ds_read_b128 v[168:171], v156 offset:1024
	global_load_lds_dwordx4 v134, s[56:57]
	s_mov_b32 m0, s42
	ds_read_b128 v[176:179], v156 offset:2048
	global_load_lds_dwordx4 v138, s[22:23]
	s_mov_b32 m0, s43
	ds_read_b128 v[180:183], v156 offset:3072
	global_load_lds_dwordx4 v140, s[22:23]
	ds_read_b128 v[184:187], v157
	ds_read_b128 v[188:191], v157 offset:1024
	ds_read_b128 v[192:195], v157 offset:2048
	ds_read_b128 v[204:207], v157 offset:3072
	s_add_u32 s24, s22, 0xffd50080
	s_addc_u32 s25, s23, -1
	s_cmpk_eq_i32 s55, 0xa8
	s_cselect_b32 s27, s19, s25
	s_cselect_b32 s26, s18, s24
	s_cselect_b32 s25, s17, s54
	s_cselect_b32 s24, s16, s53
	ds_read_b128 v[208:211], v158
	ds_read_b128 v[212:215], v158 offset:1024
	ds_read_b128 v[216:219], v158 offset:2048
	ds_read_b128 v[220:223], v158 offset:3072
	ds_read_b128 v[224:227], v158 offset:4096
	ds_read_b128 v[228:231], v158 offset:5120
	ds_read_b128 v[232:235], v158 offset:6144
	ds_read_b128 v[236:239], v158 offset:7168
	s_waitcnt vmcnt(24)
	s_waitcnt lgkmcnt(0)
	s_barrier
	v_mfma_f32_16x16x32_bf16 v[126:129], v[142:145], v[208:211], 0
	v_mfma_f32_16x16x32_bf16 v[126:129], v[168:171], v[212:215], v[126:129]
	v_mfma_f32_16x16x32_bf16 v[122:125], v[180:183], v[212:215], 0
	v_mfma_f32_16x16x32_bf16 v[122:125], v[176:179], v[208:211], v[122:125]
	v_mfma_f32_16x16x32_bf16 v[106:109], v[176:179], v[216:219], 0
	v_mfma_f32_16x16x32_bf16 v[106:109], v[180:183], v[220:223], v[106:109]
	v_mfma_f32_16x16x32_bf16 v[110:113], v[168:171], v[220:223], 0
	v_mfma_f32_16x16x32_bf16 v[110:113], v[142:145], v[216:219], v[110:113]
	v_mfma_f32_16x16x32_bf16 v[94:97], v[142:145], v[224:227], 0
	v_mfma_f32_16x16x32_bf16 v[94:97], v[168:171], v[228:231], v[94:97]
	v_mfma_f32_16x16x32_bf16 v[90:93], v[180:183], v[228:231], 0
	v_mfma_f32_16x16x32_bf16 v[90:93], v[176:179], v[224:227], v[90:93]
	v_mfma_f32_16x16x32_bf16 v[74:77], v[176:179], v[232:235], 0
	v_mfma_f32_16x16x32_bf16 v[74:77], v[180:183], v[236:239], v[74:77]
	v_mfma_f32_16x16x32_bf16 v[78:81], v[168:171], v[236:239], 0
	v_mfma_f32_16x16x32_bf16 v[78:81], v[142:145], v[232:235], v[78:81]
	v_mfma_f32_16x16x32_bf16 v[70:73], v[184:187], v[232:235], 0
	v_mfma_f32_16x16x32_bf16 v[70:73], v[188:191], v[236:239], v[70:73]
	v_mfma_f32_16x16x32_bf16 v[66:69], v[204:207], v[236:239], 0
	v_mfma_f32_16x16x32_bf16 v[66:69], v[192:195], v[232:235], v[66:69]
	v_mfma_f32_16x16x32_bf16 v[82:85], v[192:195], v[224:227], 0
	v_mfma_f32_16x16x32_bf16 v[82:85], v[204:207], v[228:231], v[82:85]
	v_mfma_f32_16x16x32_bf16 v[86:89], v[188:191], v[228:231], 0
	v_mfma_f32_16x16x32_bf16 v[86:89], v[184:187], v[224:227], v[86:89]
	v_mfma_f32_16x16x32_bf16 v[102:105], v[184:187], v[216:219], 0
	v_mfma_f32_16x16x32_bf16 v[102:105], v[188:191], v[220:223], v[102:105]
	v_mfma_f32_16x16x32_bf16 v[98:101], v[204:207], v[220:223], 0
	v_mfma_f32_16x16x32_bf16 v[98:101], v[192:195], v[216:219], v[98:101]
	v_mfma_f32_16x16x32_bf16 v[114:117], v[192:195], v[208:211], 0
	v_mfma_f32_16x16x32_bf16 v[114:117], v[204:207], v[212:215], v[114:117]
	v_mfma_f32_16x16x32_bf16 v[118:121], v[188:191], v[212:215], 0
	v_mfma_f32_16x16x32_bf16 v[118:121], v[184:187], v[208:211], v[118:121]
	s_barrier
	s_mov_b32 m0, s44
	s_add_u32 s56, s24, 0x2b0000
	global_load_lds_dwordx4 v132, s[24:25]
	s_mov_b32 m0, s45
	s_addc_u32 s57, s25, 0
	global_load_lds_dwordx4 v136, s[24:25]
	s_mov_b32 m0, s46
	ds_read_b128 v[208:211], v158 offset:16384
	global_load_lds_dwordx4 v132, s[56:57]
	s_mov_b32 m0, s47
	ds_read_b128 v[212:215], v158 offset:17408
	global_load_lds_dwordx4 v136, s[56:57]
	ds_read_b128 v[216:219], v158 offset:18432
	ds_read_b128 v[220:223], v158 offset:19456
	ds_read_b128 v[224:227], v158 offset:20480
	ds_read_b128 v[228:231], v158 offset:21504
	ds_read_b128 v[232:235], v158 offset:22528
	ds_read_b128 v[236:239], v158 offset:23552
	s_waitcnt vmcnt(6)
	s_waitcnt lgkmcnt(0)
	s_barrier
	v_mfma_f32_16x16x32_bf16 v[62:65], v[142:145], v[208:211], 0
	v_mfma_f32_16x16x32_bf16 v[62:65], v[168:171], v[212:215], v[62:65]
	v_mfma_f32_16x16x32_bf16 v[58:61], v[180:183], v[212:215], 0
	v_mfma_f32_16x16x32_bf16 v[58:61], v[176:179], v[208:211], v[58:61]
	v_mfma_f32_16x16x32_bf16 v[42:45], v[176:179], v[216:219], 0
	v_mfma_f32_16x16x32_bf16 v[42:45], v[180:183], v[220:223], v[42:45]
	v_mfma_f32_16x16x32_bf16 v[46:49], v[168:171], v[220:223], 0
	v_mfma_f32_16x16x32_bf16 v[46:49], v[142:145], v[216:219], v[46:49]
	v_mfma_f32_16x16x32_bf16 v[30:33], v[142:145], v[224:227], 0
	v_mfma_f32_16x16x32_bf16 v[30:33], v[168:171], v[228:231], v[30:33]
	v_mfma_f32_16x16x32_bf16 v[26:29], v[180:183], v[228:231], 0
	v_mfma_f32_16x16x32_bf16 v[26:29], v[176:179], v[224:227], v[26:29]
	v_mfma_f32_16x16x32_bf16 v[10:13], v[176:179], v[232:235], 0
	v_mfma_f32_16x16x32_bf16 v[10:13], v[180:183], v[236:239], v[10:13]
	v_mfma_f32_16x16x32_bf16 v[14:17], v[168:171], v[236:239], 0
	v_mfma_f32_16x16x32_bf16 v[14:17], v[142:145], v[232:235], v[14:17]
	v_mfma_f32_16x16x32_bf16 v[6:9], v[184:187], v[232:235], 0
	v_mfma_f32_16x16x32_bf16 v[6:9], v[188:191], v[236:239], v[6:9]
	v_mfma_f32_16x16x32_bf16 v[2:5], v[204:207], v[236:239], 0
	v_mfma_f32_16x16x32_bf16 v[2:5], v[192:195], v[232:235], v[2:5]
	v_mfma_f32_16x16x32_bf16 v[18:21], v[192:195], v[224:227], 0
	v_mfma_f32_16x16x32_bf16 v[18:21], v[204:207], v[228:231], v[18:21]
	v_mfma_f32_16x16x32_bf16 v[22:25], v[188:191], v[228:231], 0
	v_mfma_f32_16x16x32_bf16 v[22:25], v[184:187], v[224:227], v[22:25]
	v_mfma_f32_16x16x32_bf16 v[38:41], v[184:187], v[216:219], 0
	v_mfma_f32_16x16x32_bf16 v[38:41], v[188:191], v[220:223], v[38:41]
	v_mfma_f32_16x16x32_bf16 v[34:37], v[204:207], v[220:223], 0
	v_mfma_f32_16x16x32_bf16 v[34:37], v[192:195], v[216:219], v[34:37]
	v_mfma_f32_16x16x32_bf16 v[50:53], v[192:195], v[208:211], 0
	v_mfma_f32_16x16x32_bf16 v[50:53], v[204:207], v[212:215], v[50:53]
	v_mfma_f32_16x16x32_bf16 v[54:57], v[188:191], v[212:215], 0
	v_mfma_f32_16x16x32_bf16 v[54:57], v[184:187], v[208:211], v[54:57]
	s_barrier
	s_mov_b32 m0, s35
	ds_read_b128 v[142:145], v159
	global_load_lds_dwordx4 v130, s[26:27]
	s_mov_b32 m0, s36
	ds_read_b128 v[168:171], v159 offset:1024
	global_load_lds_dwordx4 v134, s[26:27]
	s_add_u32 s26, s26, 0x2b0000
	s_addc_u32 s27, s27, 0
	s_mov_b32 m0, s37
	ds_read_b128 v[176:179], v159 offset:2048
	global_load_lds_dwordx4 v130, s[26:27]
	s_mov_b32 m0, s38
	ds_read_b128 v[180:183], v159 offset:3072
	global_load_lds_dwordx4 v134, s[26:27]
	ds_read_b128 v[184:187], v160
	ds_read_b128 v[188:191], v160 offset:1024
	ds_read_b128 v[192:195], v160 offset:2048
	ds_read_b128 v[204:207], v160 offset:3072
	ds_read_b128 v[208:211], v158 offset:32768
	ds_read_b128 v[212:215], v158 offset:33792
	ds_read_b128 v[216:219], v158 offset:34816
	ds_read_b128 v[220:223], v158 offset:35840
	ds_read_b128 v[224:227], v158 offset:36864
	ds_read_b128 v[228:231], v158 offset:37888
	ds_read_b128 v[232:235], v158 offset:38912
	ds_read_b128 v[236:239], v158 offset:39936
	s_waitcnt vmcnt(8)
	s_waitcnt lgkmcnt(0)
	s_barrier
	v_mfma_f32_16x16x32_bf16 v[126:129], v[142:145], v[208:211], v[126:129]
	v_mfma_f32_16x16x32_bf16 v[126:129], v[168:171], v[212:215], v[126:129]
	v_mfma_f32_16x16x32_bf16 v[122:125], v[180:183], v[212:215], v[122:125]
	v_mfma_f32_16x16x32_bf16 v[122:125], v[176:179], v[208:211], v[122:125]
	v_mfma_f32_16x16x32_bf16 v[106:109], v[176:179], v[216:219], v[106:109]
	v_mfma_f32_16x16x32_bf16 v[106:109], v[180:183], v[220:223], v[106:109]
	v_mfma_f32_16x16x32_bf16 v[110:113], v[168:171], v[220:223], v[110:113]
	v_mfma_f32_16x16x32_bf16 v[110:113], v[142:145], v[216:219], v[110:113]
	v_mfma_f32_16x16x32_bf16 v[94:97], v[142:145], v[224:227], v[94:97]
	v_mfma_f32_16x16x32_bf16 v[94:97], v[168:171], v[228:231], v[94:97]
	v_mfma_f32_16x16x32_bf16 v[90:93], v[180:183], v[228:231], v[90:93]
	v_mfma_f32_16x16x32_bf16 v[90:93], v[176:179], v[224:227], v[90:93]
	v_mfma_f32_16x16x32_bf16 v[74:77], v[176:179], v[232:235], v[74:77]
	v_mfma_f32_16x16x32_bf16 v[74:77], v[180:183], v[236:239], v[74:77]
	v_mfma_f32_16x16x32_bf16 v[78:81], v[168:171], v[236:239], v[78:81]
	v_mfma_f32_16x16x32_bf16 v[78:81], v[142:145], v[232:235], v[78:81]
	v_mfma_f32_16x16x32_bf16 v[70:73], v[184:187], v[232:235], v[70:73]
	v_mfma_f32_16x16x32_bf16 v[70:73], v[188:191], v[236:239], v[70:73]
	v_mfma_f32_16x16x32_bf16 v[66:69], v[204:207], v[236:239], v[66:69]
	v_mfma_f32_16x16x32_bf16 v[66:69], v[192:195], v[232:235], v[66:69]
	v_mfma_f32_16x16x32_bf16 v[82:85], v[192:195], v[224:227], v[82:85]
	v_mfma_f32_16x16x32_bf16 v[82:85], v[204:207], v[228:231], v[82:85]
	v_mfma_f32_16x16x32_bf16 v[86:89], v[188:191], v[228:231], v[86:89]
	v_mfma_f32_16x16x32_bf16 v[86:89], v[184:187], v[224:227], v[86:89]
	v_mfma_f32_16x16x32_bf16 v[102:105], v[184:187], v[216:219], v[102:105]
	v_mfma_f32_16x16x32_bf16 v[102:105], v[188:191], v[220:223], v[102:105]
	v_mfma_f32_16x16x32_bf16 v[98:101], v[204:207], v[220:223], v[98:101]
	v_mfma_f32_16x16x32_bf16 v[98:101], v[192:195], v[216:219], v[98:101]
	v_mfma_f32_16x16x32_bf16 v[114:117], v[192:195], v[208:211], v[114:117]
	v_mfma_f32_16x16x32_bf16 v[114:117], v[204:207], v[212:215], v[114:117]
	v_mfma_f32_16x16x32_bf16 v[118:121], v[188:191], v[212:215], v[118:121]
	v_mfma_f32_16x16x32_bf16 v[118:121], v[184:187], v[208:211], v[118:121]
	s_barrier
	s_mov_b32 m0, s48
	s_add_u32 s24, s24, 0x80
	s_addc_u32 s25, s25, 0
	global_load_lds_dwordx4 v132, s[24:25]
	s_mov_b32 m0, s49
	ds_read_b128 v[208:211], v158 offset:49152
	global_load_lds_dwordx4 v136, s[24:25]
	s_mov_b32 m0, s50
	s_add_u32 s24, s24, 0x2b0000
	s_addc_u32 s25, s25, 0
	global_load_lds_dwordx4 v132, s[24:25]
	s_add_i32 m0, s50, 0x2000
	ds_read_b128 v[212:215], v158 offset:50176
	global_load_lds_dwordx4 v136, s[24:25]
	ds_read_b128 v[216:219], v158 offset:51200
	ds_read_b128 v[220:223], v158 offset:52224
	ds_read_b128 v[224:227], v158 offset:53248
	ds_read_b128 v[228:231], v158 offset:54272
	ds_read_b128 v[232:235], v158 offset:55296
	ds_read_b128 v[236:239], v158 offset:56320
	s_waitcnt vmcnt(6)
	s_waitcnt lgkmcnt(0)
	s_barrier
	v_mfma_f32_16x16x32_bf16 v[62:65], v[142:145], v[208:211], v[62:65]
	v_mfma_f32_16x16x32_bf16 v[62:65], v[168:171], v[212:215], v[62:65]
	v_mfma_f32_16x16x32_bf16 v[58:61], v[180:183], v[212:215], v[58:61]
	v_mfma_f32_16x16x32_bf16 v[58:61], v[176:179], v[208:211], v[58:61]
	v_mfma_f32_16x16x32_bf16 v[42:45], v[176:179], v[216:219], v[42:45]
	v_mfma_f32_16x16x32_bf16 v[42:45], v[180:183], v[220:223], v[42:45]
	v_mfma_f32_16x16x32_bf16 v[46:49], v[168:171], v[220:223], v[46:49]
	v_mfma_f32_16x16x32_bf16 v[46:49], v[142:145], v[216:219], v[46:49]
	v_mfma_f32_16x16x32_bf16 v[30:33], v[142:145], v[224:227], v[30:33]
	v_mfma_f32_16x16x32_bf16 v[30:33], v[168:171], v[228:231], v[30:33]
	v_mfma_f32_16x16x32_bf16 v[26:29], v[180:183], v[228:231], v[26:29]
	v_mfma_f32_16x16x32_bf16 v[26:29], v[176:179], v[224:227], v[26:29]
	v_mfma_f32_16x16x32_bf16 v[10:13], v[176:179], v[232:235], v[10:13]
	v_mfma_f32_16x16x32_bf16 v[10:13], v[180:183], v[236:239], v[10:13]
	v_mfma_f32_16x16x32_bf16 v[14:17], v[168:171], v[236:239], v[14:17]
	v_mfma_f32_16x16x32_bf16 v[14:17], v[142:145], v[232:235], v[14:17]
	v_mfma_f32_16x16x32_bf16 v[6:9], v[184:187], v[232:235], v[6:9]
	v_mfma_f32_16x16x32_bf16 v[6:9], v[188:191], v[236:239], v[6:9]
	v_mfma_f32_16x16x32_bf16 v[2:5], v[204:207], v[236:239], v[2:5]
	v_mfma_f32_16x16x32_bf16 v[2:5], v[192:195], v[232:235], v[2:5]
	v_mfma_f32_16x16x32_bf16 v[18:21], v[192:195], v[224:227], v[18:21]
	v_mfma_f32_16x16x32_bf16 v[18:21], v[204:207], v[228:231], v[18:21]
	v_mfma_f32_16x16x32_bf16 v[22:25], v[188:191], v[228:231], v[22:25]
	v_mfma_f32_16x16x32_bf16 v[22:25], v[184:187], v[224:227], v[22:25]
	v_mfma_f32_16x16x32_bf16 v[38:41], v[184:187], v[216:219], v[38:41]
	v_mfma_f32_16x16x32_bf16 v[38:41], v[188:191], v[220:223], v[38:41]
	v_mfma_f32_16x16x32_bf16 v[34:37], v[204:207], v[220:223], v[34:37]
	v_mfma_f32_16x16x32_bf16 v[34:37], v[192:195], v[216:219], v[34:37]
	v_mfma_f32_16x16x32_bf16 v[50:53], v[192:195], v[208:211], v[50:53]
	v_mfma_f32_16x16x32_bf16 v[50:53], v[204:207], v[212:215], v[50:53]
	v_mfma_f32_16x16x32_bf16 v[54:57], v[188:191], v[212:215], v[54:57]
	v_mfma_f32_16x16x32_bf16 v[54:57], v[184:187], v[208:211], v[54:57]
	s_barrier
	s_add_i32 s55, s55, 2
	s_add_u32 s22, s22, 0x100
	s_addc_u32 s23, s23, 0
	s_add_u32 s53, s53, 0x100
	s_addc_u32 s54, s54, 0

.LBB0_2229:
	s_add_i32 s35, s35, 1
	s_lshl_b32 s7, s35, 5
	s_add_i32 s7, s7, s3
	s_ashr_i32 s19, s7, 2
	s_cmp_lt_i32 s19, 16
	s_mov_b64 s[24:25], s[8:9]
	s_cselect_b64 s[8:9], -1, 0
	s_cmp_lt_i32 s7, 64
	s_mov_b64 s[22:23], s[10:11]
	s_cselect_b64 s[10:11], -1, 0
	s_and_b64 s[20:21], s[10:11], exec
	s_mov_b32 s43, s18
	s_cselect_b32 s18, s29, s18
	s_mov_b32 s42, s6
	s_cselect_b32 s6, s19, s6
	s_ashr_i32 s19, s18, 31
	s_and_b64 s[20:21], s[10:11], s[8:9]
	s_lshl_b64 s[8:9], s[18:19], 21
	v_readlane_b32 s0, v250, 46
	v_readlane_b32 s1, v250, 47
	s_add_u32 s10, s0, s8
	s_addc_u32 s11, s1, s9
	s_and_b64 s[8:9], s[20:21], exec
	s_cselect_b32 s19, s11, s23
	s_cselect_b32 s44, s10, s22
	s_ashr_i32 s7, s6, 31
	s_lshl_b64 s[8:9], s[6:7], 21
	v_readlane_b32 s0, v250, 44
	v_readlane_b32 s1, v250, 45
	s_add_u32 s8, s0, s8
	s_addc_u32 s9, s1, s9
	s_and_b64 s[26:27], s[20:21], exec
	s_cselect_b32 s7, s9, s25
	s_cselect_b32 s45, s8, s24
	s_add_u32 s22, s22, 0x100080
	s_addc_u32 s23, s23, 0
	s_add_u32 s46, s24, 0x100
	s_addc_u32 s47, s25, 0
	s_mov_b32 s48, -2
	s_waitcnt lgkmcnt(0)
	ds_read_b128 v[142:145], v154
	ds_read_b128 v[158:161], v154 offset:1024
	ds_read_b128 v[168:171], v154 offset:2048
	ds_read_b128 v[176:179], v154 offset:3072
	ds_read_b128 v[180:183], v155
	ds_read_b128 v[184:187], v155 offset:1024
	ds_read_b128 v[188:191], v155 offset:2048
	ds_read_b128 v[192:195], v155 offset:3072
	s_add_u32 s24, s22, 0xfff00080
	s_addc_u32 s25, s23, -1
	s_cmp_eq_u32 s48, 60
	s_cselect_b32 s27, s19, s25
	s_cselect_b32 s26, s44, s24
	s_cselect_b32 s25, s7, s47
	s_cselect_b32 s24, s45, s46
	s_mov_b32 m0, s40
	ds_read_b128 v[204:207], v156
	ds_read_b128 v[208:211], v156 offset:1024
	ds_read_b128 v[212:215], v156 offset:2048
	ds_read_b128 v[216:219], v156 offset:3072
	ds_read_b128 v[220:223], v156 offset:4096
	ds_read_b128 v[224:227], v156 offset:5120
	ds_read_b128 v[228:231], v156 offset:6144
	ds_read_b128 v[232:235], v156 offset:7168
	global_load_lds_dwordx4 v138, s[22:23]
	s_mov_b32 m0, s41
	s_nop 0
	global_load_lds_dwordx4 v140, s[22:23]
	s_waitcnt vmcnt(24)
	s_waitcnt lgkmcnt(0)
	s_barrier
	v_mfma_f32_16x16x32_bf16 v[126:129], v[142:145], v[204:207], 0
	v_mfma_f32_16x16x32_bf16 v[126:129], v[158:161], v[208:211], v[126:129]
	v_mfma_f32_16x16x32_bf16 v[122:125], v[176:179], v[208:211], 0
	v_mfma_f32_16x16x32_bf16 v[122:125], v[168:171], v[204:207], v[122:125]
	v_mfma_f32_16x16x32_bf16 v[106:109], v[168:171], v[212:215], 0
	v_mfma_f32_16x16x32_bf16 v[106:109], v[176:179], v[216:219], v[106:109]
	v_mfma_f32_16x16x32_bf16 v[110:113], v[158:161], v[216:219], 0
	v_mfma_f32_16x16x32_bf16 v[110:113], v[142:145], v[212:215], v[110:113]
	v_mfma_f32_16x16x32_bf16 v[94:97], v[142:145], v[220:223], 0
	v_mfma_f32_16x16x32_bf16 v[94:97], v[158:161], v[224:227], v[94:97]
	v_mfma_f32_16x16x32_bf16 v[90:93], v[176:179], v[224:227], 0
	v_mfma_f32_16x16x32_bf16 v[90:93], v[168:171], v[220:223], v[90:93]
	v_mfma_f32_16x16x32_bf16 v[74:77], v[168:171], v[228:231], 0
	v_mfma_f32_16x16x32_bf16 v[74:77], v[176:179], v[232:235], v[74:77]
	v_mfma_f32_16x16x32_bf16 v[78:81], v[158:161], v[232:235], 0
	v_mfma_f32_16x16x32_bf16 v[78:81], v[142:145], v[228:231], v[78:81]
	v_mfma_f32_16x16x32_bf16 v[70:73], v[180:183], v[228:231], 0
	v_mfma_f32_16x16x32_bf16 v[70:73], v[184:187], v[232:235], v[70:73]
	v_mfma_f32_16x16x32_bf16 v[66:69], v[192:195], v[232:235], 0
	v_mfma_f32_16x16x32_bf16 v[66:69], v[188:191], v[228:231], v[66:69]
	v_mfma_f32_16x16x32_bf16 v[82:85], v[188:191], v[220:223], 0
	v_mfma_f32_16x16x32_bf16 v[82:85], v[192:195], v[224:227], v[82:85]
	v_mfma_f32_16x16x32_bf16 v[86:89], v[184:187], v[224:227], 0
	v_mfma_f32_16x16x32_bf16 v[86:89], v[180:183], v[220:223], v[86:89]
	v_mfma_f32_16x16x32_bf16 v[102:105], v[180:183], v[212:215], 0
	v_mfma_f32_16x16x32_bf16 v[102:105], v[184:187], v[216:219], v[102:105]
	v_mfma_f32_16x16x32_bf16 v[98:101], v[192:195], v[216:219], 0
	v_mfma_f32_16x16x32_bf16 v[98:101], v[188:191], v[212:215], v[98:101]
	v_mfma_f32_16x16x32_bf16 v[114:117], v[188:191], v[204:207], 0
	v_mfma_f32_16x16x32_bf16 v[114:117], v[192:195], v[208:211], v[114:117]
	v_mfma_f32_16x16x32_bf16 v[118:121], v[184:187], v[208:211], 0
	v_mfma_f32_16x16x32_bf16 v[118:121], v[180:183], v[204:207], v[118:121]
	s_barrier
	s_add_i32 s49, s38, s28
	s_mov_b32 m0, s49
	ds_read_b128 v[204:207], v156 offset:16384
	ds_read_b128 v[208:211], v156 offset:17408
	ds_read_b128 v[212:215], v156 offset:18432
	ds_read_b128 v[216:219], v156 offset:19456
	ds_read_b128 v[220:223], v156 offset:20480
	ds_read_b128 v[224:227], v156 offset:21504
	ds_read_b128 v[228:231], v156 offset:22528
	ds_read_b128 v[232:235], v156 offset:23552
	global_load_lds_dwordx4 v132, s[24:25]
	s_add_i32 m0, s49, 0x2000
	s_add_u32 s50, s24, 0x100000
	s_addc_u32 s51, s25, 0
	s_add_i32 s49, s39, s28
	global_load_lds_dwordx4 v136, s[24:25]
	s_mov_b32 m0, s49
	s_nop 0
	global_load_lds_dwordx4 v132, s[50:51]
	s_add_i32 m0, s49, 0x2000
	s_nop 0
	global_load_lds_dwordx4 v136, s[50:51]
	s_mov_b32 m0, s30
	s_nop 0
	global_load_lds_dwordx4 v130, s[26:27]
	s_mov_b32 m0, s31
	s_nop 0
	global_load_lds_dwordx4 v134, s[26:27]
	s_waitcnt vmcnt(8)
	s_waitcnt lgkmcnt(0)
	s_barrier
	v_mfma_f32_16x16x32_bf16 v[62:65], v[142:145], v[204:207], 0
	v_mfma_f32_16x16x32_bf16 v[62:65], v[158:161], v[208:211], v[62:65]
	v_mfma_f32_16x16x32_bf16 v[58:61], v[176:179], v[208:211], 0
	v_mfma_f32_16x16x32_bf16 v[58:61], v[168:171], v[204:207], v[58:61]
	v_mfma_f32_16x16x32_bf16 v[42:45], v[168:171], v[212:215], 0
	v_mfma_f32_16x16x32_bf16 v[42:45], v[176:179], v[216:219], v[42:45]
	v_mfma_f32_16x16x32_bf16 v[46:49], v[158:161], v[216:219], 0
	v_mfma_f32_16x16x32_bf16 v[46:49], v[142:145], v[212:215], v[46:49]
	v_mfma_f32_16x16x32_bf16 v[30:33], v[142:145], v[220:223], 0
	v_mfma_f32_16x16x32_bf16 v[30:33], v[158:161], v[224:227], v[30:33]
	v_mfma_f32_16x16x32_bf16 v[26:29], v[176:179], v[224:227], 0
	v_mfma_f32_16x16x32_bf16 v[26:29], v[168:171], v[220:223], v[26:29]
	v_mfma_f32_16x16x32_bf16 v[10:13], v[168:171], v[228:231], 0
	v_mfma_f32_16x16x32_bf16 v[10:13], v[176:179], v[232:235], v[10:13]
	v_mfma_f32_16x16x32_bf16 v[14:17], v[158:161], v[232:235], 0
	v_mfma_f32_16x16x32_bf16 v[14:17], v[142:145], v[228:231], v[14:17]
	v_mfma_f32_16x16x32_bf16 v[6:9], v[180:183], v[228:231], 0
	v_mfma_f32_16x16x32_bf16 v[6:9], v[184:187], v[232:235], v[6:9]
	v_mfma_f32_16x16x32_bf16 v[2:5], v[192:195], v[232:235], 0
	v_mfma_f32_16x16x32_bf16 v[2:5], v[188:191], v[228:231], v[2:5]
	v_mfma_f32_16x16x32_bf16 v[18:21], v[188:191], v[220:223], 0
	v_mfma_f32_16x16x32_bf16 v[18:21], v[192:195], v[224:227], v[18:21]
	v_mfma_f32_16x16x32_bf16 v[22:25], v[184:187], v[224:227], 0
	v_mfma_f32_16x16x32_bf16 v[22:25], v[180:183], v[220:223], v[22:25]
	v_mfma_f32_16x16x32_bf16 v[38:41], v[180:183], v[212:215], 0
	v_mfma_f32_16x16x32_bf16 v[38:41], v[184:187], v[216:219], v[38:41]
	v_mfma_f32_16x16x32_bf16 v[34:37], v[192:195], v[216:219], 0
	v_mfma_f32_16x16x32_bf16 v[34:37], v[188:191], v[212:215], v[34:37]
	v_mfma_f32_16x16x32_bf16 v[50:53], v[188:191], v[204:207], 0
	v_mfma_f32_16x16x32_bf16 v[50:53], v[192:195], v[208:211], v[50:53]
	v_mfma_f32_16x16x32_bf16 v[54:57], v[184:187], v[208:211], 0
	v_mfma_f32_16x16x32_bf16 v[54:57], v[180:183], v[204:207], v[54:57]
	s_barrier
	s_add_i32 s49, 0, 0x18000
	v_add_u32_e32 v157, s49, v152
	s_add_i32 s50, 0, 0x1c000
	ds_read_b128 v[142:145], v157
	ds_read_b128 v[158:161], v157 offset:1024
	ds_read_b128 v[168:171], v157 offset:2048
	ds_read_b128 v[176:179], v157 offset:3072
	v_add_u32_e32 v157, s50, v152
	ds_read_b128 v[180:183], v157
	ds_read_b128 v[184:187], v157 offset:1024
	ds_read_b128 v[188:191], v157 offset:2048
	ds_read_b128 v[192:195], v157 offset:3072
	s_add_u32 s26, s26, 0x100000
	s_addc_u32 s27, s27, 0
	s_mov_b32 m0, s33
	ds_read_b128 v[204:207], v156 offset:32768
	ds_read_b128 v[208:211], v156 offset:33792
	ds_read_b128 v[212:215], v156 offset:34816
	ds_read_b128 v[216:219], v156 offset:35840
	ds_read_b128 v[220:223], v156 offset:36864
	ds_read_b128 v[224:227], v156 offset:37888
	ds_read_b128 v[228:231], v156 offset:38912
	ds_read_b128 v[232:235], v156 offset:39936
	global_load_lds_dwordx4 v130, s[26:27]
	s_mov_b32 m0, s34
	s_nop 0
	global_load_lds_dwordx4 v134, s[26:27]
	s_waitcnt vmcnt(8)
	s_waitcnt lgkmcnt(0)
	s_barrier
	v_mfma_f32_16x16x32_bf16 v[126:129], v[142:145], v[204:207], v[126:129]
	v_mfma_f32_16x16x32_bf16 v[126:129], v[158:161], v[208:211], v[126:129]
	v_mfma_f32_16x16x32_bf16 v[122:125], v[176:179], v[208:211], v[122:125]
	v_mfma_f32_16x16x32_bf16 v[122:125], v[168:171], v[204:207], v[122:125]
	v_mfma_f32_16x16x32_bf16 v[106:109], v[168:171], v[212:215], v[106:109]
	v_mfma_f32_16x16x32_bf16 v[106:109], v[176:179], v[216:219], v[106:109]
	v_mfma_f32_16x16x32_bf16 v[110:113], v[158:161], v[216:219], v[110:113]
	v_mfma_f32_16x16x32_bf16 v[110:113], v[142:145], v[212:215], v[110:113]
	v_mfma_f32_16x16x32_bf16 v[94:97], v[142:145], v[220:223], v[94:97]
	v_mfma_f32_16x16x32_bf16 v[94:97], v[158:161], v[224:227], v[94:97]
	v_mfma_f32_16x16x32_bf16 v[90:93], v[176:179], v[224:227], v[90:93]
	v_mfma_f32_16x16x32_bf16 v[90:93], v[168:171], v[220:223], v[90:93]
	v_mfma_f32_16x16x32_bf16 v[74:77], v[168:171], v[228:231], v[74:77]
	v_mfma_f32_16x16x32_bf16 v[74:77], v[176:179], v[232:235], v[74:77]
	v_mfma_f32_16x16x32_bf16 v[78:81], v[158:161], v[232:235], v[78:81]
	v_mfma_f32_16x16x32_bf16 v[78:81], v[142:145], v[228:231], v[78:81]
	v_mfma_f32_16x16x32_bf16 v[70:73], v[180:183], v[228:231], v[70:73]
	v_mfma_f32_16x16x32_bf16 v[70:73], v[184:187], v[232:235], v[70:73]
	v_mfma_f32_16x16x32_bf16 v[66:69], v[192:195], v[232:235], v[66:69]
	v_mfma_f32_16x16x32_bf16 v[66:69], v[188:191], v[228:231], v[66:69]
	v_mfma_f32_16x16x32_bf16 v[82:85], v[188:191], v[220:223], v[82:85]
	v_mfma_f32_16x16x32_bf16 v[82:85], v[192:195], v[224:227], v[82:85]
	v_mfma_f32_16x16x32_bf16 v[86:89], v[184:187], v[224:227], v[86:89]
	v_mfma_f32_16x16x32_bf16 v[86:89], v[180:183], v[220:223], v[86:89]
	v_mfma_f32_16x16x32_bf16 v[102:105], v[180:183], v[212:215], v[102:105]
	v_mfma_f32_16x16x32_bf16 v[102:105], v[184:187], v[216:219], v[102:105]
	v_mfma_f32_16x16x32_bf16 v[98:101], v[192:195], v[216:219], v[98:101]
	v_mfma_f32_16x16x32_bf16 v[98:101], v[188:191], v[212:215], v[98:101]
	v_mfma_f32_16x16x32_bf16 v[114:117], v[188:191], v[204:207], v[114:117]
	v_mfma_f32_16x16x32_bf16 v[114:117], v[192:195], v[208:211], v[114:117]
	v_mfma_f32_16x16x32_bf16 v[118:121], v[184:187], v[208:211], v[118:121]
	v_mfma_f32_16x16x32_bf16 v[118:121], v[180:183], v[204:207], v[118:121]
	s_barrier
	s_add_u32 s98, s26, 0xfff00080
	s_addc_u32 s99, s27, -1
	s_add_u32 s24, s24, 0x80
	s_addc_u32 s25, s25, 0
	s_add_i32 s26, s49, s28
	s_mov_b32 m0, s26
	ds_read_b128 v[204:207], v156 offset:49152
	ds_read_b128 v[208:211], v156 offset:50176
	ds_read_b128 v[212:215], v156 offset:51200
	ds_read_b128 v[216:219], v156 offset:52224
	ds_read_b128 v[220:223], v156 offset:53248
	ds_read_b128 v[224:227], v156 offset:54272
	ds_read_b128 v[228:231], v156 offset:55296
	ds_read_b128 v[232:235], v156 offset:56320
	global_load_lds_dwordx4 v132, s[24:25]
	s_add_i32 m0, s26, 0x2000
	s_add_i32 s26, s50, s28
	global_load_lds_dwordx4 v136, s[24:25]
	s_add_u32 s24, s24, 0x100000
	s_addc_u32 s25, s25, 0
	s_mov_b32 m0, s26
	s_nop 0
	global_load_lds_dwordx4 v132, s[24:25]
	s_add_i32 m0, s26, 0x2000
	s_nop 0
	global_load_lds_dwordx4 v136, s[24:25]
	s_mov_b32 m0, s36
	s_nop 0
	global_load_lds_dwordx4 v130, s[98:99]
	s_mov_b32 m0, s37
	s_nop 0
	global_load_lds_dwordx4 v134, s[98:99]
	s_waitcnt vmcnt(8)
	s_waitcnt lgkmcnt(0)
	s_barrier
	v_mfma_f32_16x16x32_bf16 v[62:65], v[142:145], v[204:207], v[62:65]
	v_mfma_f32_16x16x32_bf16 v[62:65], v[158:161], v[208:211], v[62:65]
	v_mfma_f32_16x16x32_bf16 v[58:61], v[176:179], v[208:211], v[58:61]
	v_mfma_f32_16x16x32_bf16 v[58:61], v[168:171], v[204:207], v[58:61]
	v_mfma_f32_16x16x32_bf16 v[42:45], v[168:171], v[212:215], v[42:45]
	v_mfma_f32_16x16x32_bf16 v[42:45], v[176:179], v[216:219], v[42:45]
	v_mfma_f32_16x16x32_bf16 v[46:49], v[158:161], v[216:219], v[46:49]
	v_mfma_f32_16x16x32_bf16 v[46:49], v[142:145], v[212:215], v[46:49]
	v_mfma_f32_16x16x32_bf16 v[30:33], v[142:145], v[220:223], v[30:33]
	v_mfma_f32_16x16x32_bf16 v[30:33], v[158:161], v[224:227], v[30:33]
	v_mfma_f32_16x16x32_bf16 v[26:29], v[176:179], v[224:227], v[26:29]
	v_mfma_f32_16x16x32_bf16 v[26:29], v[168:171], v[220:223], v[26:29]
	v_mfma_f32_16x16x32_bf16 v[10:13], v[168:171], v[228:231], v[10:13]
	v_mfma_f32_16x16x32_bf16 v[10:13], v[176:179], v[232:235], v[10:13]
	v_mfma_f32_16x16x32_bf16 v[14:17], v[158:161], v[232:235], v[14:17]
	v_mfma_f32_16x16x32_bf16 v[14:17], v[142:145], v[228:231], v[14:17]
	v_mfma_f32_16x16x32_bf16 v[6:9], v[180:183], v[228:231], v[6:9]
	v_mfma_f32_16x16x32_bf16 v[6:9], v[184:187], v[232:235], v[6:9]
	v_mfma_f32_16x16x32_bf16 v[2:5], v[192:195], v[232:235], v[2:5]
	v_mfma_f32_16x16x32_bf16 v[2:5], v[188:191], v[228:231], v[2:5]
	v_mfma_f32_16x16x32_bf16 v[18:21], v[188:191], v[220:223], v[18:21]
	v_mfma_f32_16x16x32_bf16 v[18:21], v[192:195], v[224:227], v[18:21]
	v_mfma_f32_16x16x32_bf16 v[22:25], v[184:187], v[224:227], v[22:25]
	v_mfma_f32_16x16x32_bf16 v[22:25], v[180:183], v[220:223], v[22:25]
	v_mfma_f32_16x16x32_bf16 v[38:41], v[180:183], v[212:215], v[38:41]
	v_mfma_f32_16x16x32_bf16 v[38:41], v[184:187], v[216:219], v[38:41]
	v_mfma_f32_16x16x32_bf16 v[34:37], v[192:195], v[216:219], v[34:37]
	v_mfma_f32_16x16x32_bf16 v[34:37], v[188:191], v[212:215], v[34:37]
	v_mfma_f32_16x16x32_bf16 v[50:53], v[188:191], v[204:207], v[50:53]
	v_mfma_f32_16x16x32_bf16 v[50:53], v[192:195], v[208:211], v[50:53]
	v_mfma_f32_16x16x32_bf16 v[54:57], v[184:187], v[208:211], v[54:57]
	v_mfma_f32_16x16x32_bf16 v[54:57], v[180:183], v[204:207], v[54:57]
	s_barrier
	s_add_i32 s48, s48, 2
	s_add_u32 s22, s22, 0x100
	s_addc_u32 s23, s23, 0
	s_add_u32 s46, s46, 0x100
	s_addc_u32 s47, s47, 0

.LBB0_2372:
	s_add_i32 s34, s34, 1
	s_mov_b32 s50, s6
	s_lshl_b32 s6, s34, 5
	s_add_i32 s6, s6, s3
	s_mov_b64 s[22:23], s[8:9]
	s_lshl_b32 s8, s6, 3
	s_ashr_i32 s7, s6, 2
	s_add_i32 s8, s8, s37
	s_cmpk_lt_i32 s6, 0x158
	s_cselect_b32 s6, s7, s8
	s_mov_b32 s51, s26
	s_cselect_b32 s26, s38, 32
	s_cmpk_lt_i32 s6, 0x56
	s_cselect_b64 s[18:19], -1, 0
	s_lshl_b32 s7, s26, 21
	v_readlane_b32 s0, v250, 46
	s_mov_b64 s[20:21], s[10:11]
	v_readlane_b32 s1, v250, 47
	s_add_u32 s10, s0, s7
	s_addc_u32 s11, s1, 0
	s_and_b64 s[8:9], s[18:19], exec
	s_cselect_b32 s52, s11, s21
	s_cselect_b32 s53, s10, s20
	s_ashr_i32 s7, s6, 31
	s_lshl_b64 s[8:9], s[6:7], 21
	s_add_u32 s8, s27, s8
	s_addc_u32 s9, s28, s9
	s_and_b64 s[24:25], s[18:19], exec
	s_cselect_b32 s7, s9, s23
	s_cselect_b32 s54, s8, s22
	s_add_u32 s20, s20, 0x100080
	s_addc_u32 s21, s21, 0
	s_add_u32 s55, s22, 0x100
	s_addc_u32 s56, s23, 0
	s_mov_b32 s57, -2
	s_waitcnt lgkmcnt(0)
	s_add_u32 s60, s20, 0xfff00000
	s_addc_u32 s61, s21, -1
	s_mov_b32 m0, s35
	ds_read_b128 v[142:145], v148
	global_load_lds_dwordx4 v130, s[60:61]
	s_mov_b32 m0, s36
	ds_read_b128 v[154:157], v148 offset:1024
	global_load_lds_dwordx4 v134, s[60:61]
	s_mov_b32 m0, s40
	ds_read_b128 v[158:161], v148 offset:2048
	global_load_lds_dwordx4 v138, s[20:21]
	s_mov_b32 m0, s41
	ds_read_b128 v[168:171], v148 offset:3072
	global_load_lds_dwordx4 v140, s[20:21]
	ds_read_b128 v[176:179], v149
	ds_read_b128 v[180:183], v149 offset:1024
	ds_read_b128 v[184:187], v149 offset:2048
	ds_read_b128 v[188:191], v149 offset:3072
	s_add_u32 s22, s20, 0xfff00080
	s_addc_u32 s23, s21, -1
	s_cmp_eq_u32 s57, 60
	s_cselect_b32 s25, s52, s23
	s_cselect_b32 s24, s53, s22
	s_cselect_b32 s23, s7, s56
	s_cselect_b32 s22, s54, s55
	ds_read_b128 v[192:195], v150
	ds_read_b128 v[204:207], v150 offset:1024
	ds_read_b128 v[208:211], v150 offset:2048
	ds_read_b128 v[212:215], v150 offset:3072
	ds_read_b128 v[216:219], v150 offset:4096
	ds_read_b128 v[220:223], v150 offset:5120
	ds_read_b128 v[224:227], v150 offset:6144
	ds_read_b128 v[228:231], v150 offset:7168
	s_waitcnt vmcnt(16)
	s_waitcnt lgkmcnt(0)
	s_barrier
	v_mfma_f32_16x16x32_bf16 v[126:129], v[142:145], v[192:195], 0
	v_mfma_f32_16x16x32_bf16 v[126:129], v[154:157], v[204:207], v[126:129]
	v_mfma_f32_16x16x32_bf16 v[122:125], v[168:171], v[204:207], 0
	v_mfma_f32_16x16x32_bf16 v[122:125], v[158:161], v[192:195], v[122:125]
	v_mfma_f32_16x16x32_bf16 v[106:109], v[158:161], v[208:211], 0
	v_mfma_f32_16x16x32_bf16 v[106:109], v[168:171], v[212:215], v[106:109]
	v_mfma_f32_16x16x32_bf16 v[110:113], v[154:157], v[212:215], 0
	v_mfma_f32_16x16x32_bf16 v[110:113], v[142:145], v[208:211], v[110:113]
	v_mfma_f32_16x16x32_bf16 v[94:97], v[142:145], v[216:219], 0
	v_mfma_f32_16x16x32_bf16 v[94:97], v[154:157], v[220:223], v[94:97]
	v_mfma_f32_16x16x32_bf16 v[90:93], v[168:171], v[220:223], 0
	v_mfma_f32_16x16x32_bf16 v[90:93], v[158:161], v[216:219], v[90:93]
	v_mfma_f32_16x16x32_bf16 v[74:77], v[158:161], v[224:227], 0
	v_mfma_f32_16x16x32_bf16 v[74:77], v[168:171], v[228:231], v[74:77]
	v_mfma_f32_16x16x32_bf16 v[78:81], v[154:157], v[228:231], 0
	v_mfma_f32_16x16x32_bf16 v[78:81], v[142:145], v[224:227], v[78:81]
	v_mfma_f32_16x16x32_bf16 v[70:73], v[176:179], v[224:227], 0
	v_mfma_f32_16x16x32_bf16 v[70:73], v[180:183], v[228:231], v[70:73]
	v_mfma_f32_16x16x32_bf16 v[66:69], v[188:191], v[228:231], 0
	v_mfma_f32_16x16x32_bf16 v[66:69], v[184:187], v[224:227], v[66:69]
	v_mfma_f32_16x16x32_bf16 v[82:85], v[184:187], v[216:219], 0
	v_mfma_f32_16x16x32_bf16 v[82:85], v[188:191], v[220:223], v[82:85]
	v_mfma_f32_16x16x32_bf16 v[86:89], v[180:183], v[220:223], 0
	v_mfma_f32_16x16x32_bf16 v[86:89], v[176:179], v[216:219], v[86:89]
	v_mfma_f32_16x16x32_bf16 v[102:105], v[176:179], v[208:211], 0
	v_mfma_f32_16x16x32_bf16 v[102:105], v[180:183], v[212:215], v[102:105]
	v_mfma_f32_16x16x32_bf16 v[98:101], v[188:191], v[212:215], 0
	v_mfma_f32_16x16x32_bf16 v[98:101], v[184:187], v[208:211], v[98:101]
	v_mfma_f32_16x16x32_bf16 v[114:117], v[184:187], v[192:195], 0
	v_mfma_f32_16x16x32_bf16 v[114:117], v[188:191], v[204:207], v[114:117]
	v_mfma_f32_16x16x32_bf16 v[118:121], v[180:183], v[204:207], 0
	v_mfma_f32_16x16x32_bf16 v[118:121], v[176:179], v[192:195], v[118:121]
	s_barrier
	s_mov_b32 m0, s42
	s_add_u32 s60, s22, 0x100000
	global_load_lds_dwordx4 v132, s[22:23]
	s_mov_b32 m0, s43
	s_addc_u32 s61, s23, 0
	global_load_lds_dwordx4 v136, s[22:23]
	s_mov_b32 m0, s44
	ds_read_b128 v[192:195], v150 offset:16384
	global_load_lds_dwordx4 v132, s[60:61]
	s_mov_b32 m0, s45
	ds_read_b128 v[204:207], v150 offset:17408
	global_load_lds_dwordx4 v136, s[60:61]
	ds_read_b128 v[208:211], v150 offset:18432
	ds_read_b128 v[212:215], v150 offset:19456
	ds_read_b128 v[216:219], v150 offset:20480
	ds_read_b128 v[220:223], v150 offset:21504
	ds_read_b128 v[224:227], v150 offset:22528
	ds_read_b128 v[228:231], v150 offset:23552
	s_waitcnt vmcnt(6)
	s_waitcnt lgkmcnt(0)
	s_barrier
	v_mfma_f32_16x16x32_bf16 v[62:65], v[142:145], v[192:195], 0
	v_mfma_f32_16x16x32_bf16 v[62:65], v[154:157], v[204:207], v[62:65]
	v_mfma_f32_16x16x32_bf16 v[58:61], v[168:171], v[204:207], 0
	v_mfma_f32_16x16x32_bf16 v[58:61], v[158:161], v[192:195], v[58:61]
	v_mfma_f32_16x16x32_bf16 v[42:45], v[158:161], v[208:211], 0
	v_mfma_f32_16x16x32_bf16 v[42:45], v[168:171], v[212:215], v[42:45]
	v_mfma_f32_16x16x32_bf16 v[46:49], v[154:157], v[212:215], 0
	v_mfma_f32_16x16x32_bf16 v[46:49], v[142:145], v[208:211], v[46:49]
	v_mfma_f32_16x16x32_bf16 v[30:33], v[142:145], v[216:219], 0
	v_mfma_f32_16x16x32_bf16 v[30:33], v[154:157], v[220:223], v[30:33]
	v_mfma_f32_16x16x32_bf16 v[26:29], v[168:171], v[220:223], 0
	v_mfma_f32_16x16x32_bf16 v[26:29], v[158:161], v[216:219], v[26:29]
	v_mfma_f32_16x16x32_bf16 v[10:13], v[158:161], v[224:227], 0
	v_mfma_f32_16x16x32_bf16 v[10:13], v[168:171], v[228:231], v[10:13]
	v_mfma_f32_16x16x32_bf16 v[14:17], v[154:157], v[228:231], 0
	v_mfma_f32_16x16x32_bf16 v[14:17], v[142:145], v[224:227], v[14:17]
	v_mfma_f32_16x16x32_bf16 v[6:9], v[176:179], v[224:227], 0
	v_mfma_f32_16x16x32_bf16 v[6:9], v[180:183], v[228:231], v[6:9]
	v_mfma_f32_16x16x32_bf16 v[2:5], v[188:191], v[228:231], 0
	v_mfma_f32_16x16x32_bf16 v[2:5], v[184:187], v[224:227], v[2:5]
	v_mfma_f32_16x16x32_bf16 v[18:21], v[184:187], v[216:219], 0
	v_mfma_f32_16x16x32_bf16 v[18:21], v[188:191], v[220:223], v[18:21]
	v_mfma_f32_16x16x32_bf16 v[22:25], v[180:183], v[220:223], 0
	v_mfma_f32_16x16x32_bf16 v[22:25], v[176:179], v[216:219], v[22:25]
	v_mfma_f32_16x16x32_bf16 v[38:41], v[176:179], v[208:211], 0
	v_mfma_f32_16x16x32_bf16 v[38:41], v[180:183], v[212:215], v[38:41]
	v_mfma_f32_16x16x32_bf16 v[34:37], v[188:191], v[212:215], 0
	v_mfma_f32_16x16x32_bf16 v[34:37], v[184:187], v[208:211], v[34:37]
	v_mfma_f32_16x16x32_bf16 v[50:53], v[184:187], v[192:195], 0
	v_mfma_f32_16x16x32_bf16 v[50:53], v[188:191], v[204:207], v[50:53]
	v_mfma_f32_16x16x32_bf16 v[54:57], v[180:183], v[204:207], 0
	v_mfma_f32_16x16x32_bf16 v[54:57], v[176:179], v[192:195], v[54:57]
	s_barrier
	s_mov_b32 m0, s29
	ds_read_b128 v[142:145], v151
	global_load_lds_dwordx4 v130, s[24:25]
	s_mov_b32 m0, s30
	ds_read_b128 v[154:157], v151 offset:1024
	global_load_lds_dwordx4 v134, s[24:25]
	s_add_u32 s24, s24, 0x100000
	s_addc_u32 s25, s25, 0
	s_mov_b32 m0, s31
	ds_read_b128 v[158:161], v151 offset:2048
	global_load_lds_dwordx4 v130, s[24:25]
	s_mov_b32 m0, s33
	ds_read_b128 v[168:171], v151 offset:3072
	global_load_lds_dwordx4 v134, s[24:25]
	ds_read_b128 v[176:179], v152
	ds_read_b128 v[180:183], v152 offset:1024
	ds_read_b128 v[184:187], v152 offset:2048
	ds_read_b128 v[188:191], v152 offset:3072
	ds_read_b128 v[192:195], v150 offset:32768
	ds_read_b128 v[204:207], v150 offset:33792
	ds_read_b128 v[208:211], v150 offset:34816
	ds_read_b128 v[212:215], v150 offset:35840
	ds_read_b128 v[216:219], v150 offset:36864
	ds_read_b128 v[220:223], v150 offset:37888
	ds_read_b128 v[224:227], v150 offset:38912
	ds_read_b128 v[228:231], v150 offset:39936
	s_waitcnt vmcnt(8)
	s_waitcnt lgkmcnt(0)
	s_barrier
	v_mfma_f32_16x16x32_bf16 v[126:129], v[142:145], v[192:195], v[126:129]
	v_mfma_f32_16x16x32_bf16 v[126:129], v[154:157], v[204:207], v[126:129]
	v_mfma_f32_16x16x32_bf16 v[122:125], v[168:171], v[204:207], v[122:125]
	v_mfma_f32_16x16x32_bf16 v[122:125], v[158:161], v[192:195], v[122:125]
	v_mfma_f32_16x16x32_bf16 v[106:109], v[158:161], v[208:211], v[106:109]
	v_mfma_f32_16x16x32_bf16 v[106:109], v[168:171], v[212:215], v[106:109]
	v_mfma_f32_16x16x32_bf16 v[110:113], v[154:157], v[212:215], v[110:113]
	v_mfma_f32_16x16x32_bf16 v[110:113], v[142:145], v[208:211], v[110:113]
	v_mfma_f32_16x16x32_bf16 v[94:97], v[142:145], v[216:219], v[94:97]
	v_mfma_f32_16x16x32_bf16 v[94:97], v[154:157], v[220:223], v[94:97]
	v_mfma_f32_16x16x32_bf16 v[90:93], v[168:171], v[220:223], v[90:93]
	v_mfma_f32_16x16x32_bf16 v[90:93], v[158:161], v[216:219], v[90:93]
	v_mfma_f32_16x16x32_bf16 v[74:77], v[158:161], v[224:227], v[74:77]
	v_mfma_f32_16x16x32_bf16 v[74:77], v[168:171], v[228:231], v[74:77]
	v_mfma_f32_16x16x32_bf16 v[78:81], v[154:157], v[228:231], v[78:81]
	v_mfma_f32_16x16x32_bf16 v[78:81], v[142:145], v[224:227], v[78:81]
	v_mfma_f32_16x16x32_bf16 v[70:73], v[176:179], v[224:227], v[70:73]
	v_mfma_f32_16x16x32_bf16 v[70:73], v[180:183], v[228:231], v[70:73]
	v_mfma_f32_16x16x32_bf16 v[66:69], v[188:191], v[228:231], v[66:69]
	v_mfma_f32_16x16x32_bf16 v[66:69], v[184:187], v[224:227], v[66:69]
	v_mfma_f32_16x16x32_bf16 v[82:85], v[184:187], v[216:219], v[82:85]
	v_mfma_f32_16x16x32_bf16 v[82:85], v[188:191], v[220:223], v[82:85]
	v_mfma_f32_16x16x32_bf16 v[86:89], v[180:183], v[220:223], v[86:89]
	v_mfma_f32_16x16x32_bf16 v[86:89], v[176:179], v[216:219], v[86:89]
	v_mfma_f32_16x16x32_bf16 v[102:105], v[176:179], v[208:211], v[102:105]
	v_mfma_f32_16x16x32_bf16 v[102:105], v[180:183], v[212:215], v[102:105]
	v_mfma_f32_16x16x32_bf16 v[98:101], v[188:191], v[212:215], v[98:101]
	v_mfma_f32_16x16x32_bf16 v[98:101], v[184:187], v[208:211], v[98:101]
	v_mfma_f32_16x16x32_bf16 v[114:117], v[184:187], v[192:195], v[114:117]
	v_mfma_f32_16x16x32_bf16 v[114:117], v[188:191], v[204:207], v[114:117]
	v_mfma_f32_16x16x32_bf16 v[118:121], v[180:183], v[204:207], v[118:121]
	v_mfma_f32_16x16x32_bf16 v[118:121], v[176:179], v[192:195], v[118:121]
	s_barrier
	s_mov_b32 m0, s46
	s_add_u32 s22, s22, 0x80
	s_addc_u32 s23, s23, 0
	global_load_lds_dwordx4 v132, s[22:23]
	s_mov_b32 m0, s47
	ds_read_b128 v[192:195], v150 offset:49152
	global_load_lds_dwordx4 v136, s[22:23]
	s_mov_b32 m0, s48
	s_add_u32 s22, s22, 0x100000
	s_addc_u32 s23, s23, 0
	global_load_lds_dwordx4 v132, s[22:23]
	s_mov_b32 m0, s49
	ds_read_b128 v[204:207], v150 offset:50176
	global_load_lds_dwordx4 v136, s[22:23]
	ds_read_b128 v[208:211], v150 offset:51200
	ds_read_b128 v[212:215], v150 offset:52224
	ds_read_b128 v[216:219], v150 offset:53248
	ds_read_b128 v[220:223], v150 offset:54272
	ds_read_b128 v[224:227], v150 offset:55296
	ds_read_b128 v[228:231], v150 offset:56320
	s_waitcnt vmcnt(6)
	s_waitcnt lgkmcnt(0)
	s_barrier
	v_mfma_f32_16x16x32_bf16 v[62:65], v[142:145], v[192:195], v[62:65]
	v_mfma_f32_16x16x32_bf16 v[62:65], v[154:157], v[204:207], v[62:65]
	v_mfma_f32_16x16x32_bf16 v[58:61], v[168:171], v[204:207], v[58:61]
	v_mfma_f32_16x16x32_bf16 v[58:61], v[158:161], v[192:195], v[58:61]
	v_mfma_f32_16x16x32_bf16 v[42:45], v[158:161], v[208:211], v[42:45]
	v_mfma_f32_16x16x32_bf16 v[42:45], v[168:171], v[212:215], v[42:45]
	v_mfma_f32_16x16x32_bf16 v[46:49], v[154:157], v[212:215], v[46:49]
	v_mfma_f32_16x16x32_bf16 v[46:49], v[142:145], v[208:211], v[46:49]
	v_mfma_f32_16x16x32_bf16 v[30:33], v[142:145], v[216:219], v[30:33]
	v_mfma_f32_16x16x32_bf16 v[30:33], v[154:157], v[220:223], v[30:33]
	v_mfma_f32_16x16x32_bf16 v[26:29], v[168:171], v[220:223], v[26:29]
	v_mfma_f32_16x16x32_bf16 v[26:29], v[158:161], v[216:219], v[26:29]
	v_mfma_f32_16x16x32_bf16 v[10:13], v[158:161], v[224:227], v[10:13]
	v_mfma_f32_16x16x32_bf16 v[10:13], v[168:171], v[228:231], v[10:13]
	v_mfma_f32_16x16x32_bf16 v[14:17], v[154:157], v[228:231], v[14:17]
	v_mfma_f32_16x16x32_bf16 v[14:17], v[142:145], v[224:227], v[14:17]
	v_mfma_f32_16x16x32_bf16 v[6:9], v[176:179], v[224:227], v[6:9]
	v_mfma_f32_16x16x32_bf16 v[6:9], v[180:183], v[228:231], v[6:9]
	v_mfma_f32_16x16x32_bf16 v[2:5], v[188:191], v[228:231], v[2:5]
	v_mfma_f32_16x16x32_bf16 v[2:5], v[184:187], v[224:227], v[2:5]
	v_mfma_f32_16x16x32_bf16 v[18:21], v[184:187], v[216:219], v[18:21]
	v_mfma_f32_16x16x32_bf16 v[18:21], v[188:191], v[220:223], v[18:21]
	v_mfma_f32_16x16x32_bf16 v[22:25], v[180:183], v[220:223], v[22:25]
	v_mfma_f32_16x16x32_bf16 v[22:25], v[176:179], v[216:219], v[22:25]
	v_mfma_f32_16x16x32_bf16 v[38:41], v[176:179], v[208:211], v[38:41]
	v_mfma_f32_16x16x32_bf16 v[38:41], v[180:183], v[212:215], v[38:41]
	v_mfma_f32_16x16x32_bf16 v[34:37], v[188:191], v[212:215], v[34:37]
	v_mfma_f32_16x16x32_bf16 v[34:37], v[184:187], v[208:211], v[34:37]
	v_mfma_f32_16x16x32_bf16 v[50:53], v[184:187], v[192:195], v[50:53]
	v_mfma_f32_16x16x32_bf16 v[50:53], v[188:191], v[204:207], v[50:53]
	v_mfma_f32_16x16x32_bf16 v[54:57], v[180:183], v[204:207], v[54:57]
	v_mfma_f32_16x16x32_bf16 v[54:57], v[176:179], v[192:195], v[54:57]
	s_barrier
	s_add_i32 s57, s57, 2
	s_add_u32 s20, s20, 0x100
	s_addc_u32 s21, s21, 0
	s_add_u32 s55, s55, 0x100
	s_addc_u32 s56, s56, 0

.LBB0_2617:
	s_and_b64 s[24:25], s[24:25], exec
	s_cselect_b32 s25, s7, s29
	s_cselect_b32 s24, s6, s28
	s_add_u32 s28, s28, 0x2b0080
	s_addc_u32 s29, s29, 0
	s_add_u32 s60, s30, 0x100
	s_addc_u32 s61, s31, 0
	s_mov_b32 s62, -2
	s_waitcnt lgkmcnt(0)
	s_add_u32 s64, s28, 0xffd50000
	s_addc_u32 s65, s29, -1
	s_mov_b32 m0, s44
	ds_read_b128 v[142:145], v156
	global_load_lds_dwordx4 v130, s[64:65]
	s_mov_b32 m0, s45
	ds_read_b128 v[168:171], v156 offset:1024
	global_load_lds_dwordx4 v134, s[64:65]
	s_mov_b32 m0, s46
	ds_read_b128 v[172:175], v156 offset:2048
	global_load_lds_dwordx4 v138, s[28:29]
	s_mov_b32 m0, s47
	ds_read_b128 v[176:179], v156 offset:3072
	global_load_lds_dwordx4 v140, s[28:29]
	ds_read_b128 v[180:183], v157
	ds_read_b128 v[184:187], v157 offset:1024
	ds_read_b128 v[188:191], v157 offset:2048
	ds_read_b128 v[192:195], v157 offset:3072
	s_add_u32 s30, s28, 0xffd50080
	s_addc_u32 s31, s29, -1
	s_cmpk_eq_i32 s62, 0xa8
	s_cselect_b32 s35, s25, s31
	s_cselect_b32 s34, s24, s30
	s_cselect_b32 s31, s23, s61
	s_cselect_b32 s30, s22, s60
	ds_read_b128 v[196:199], v158
	ds_read_b128 v[200:203], v158 offset:1024
	ds_read_b128 v[204:207], v158 offset:2048
	ds_read_b128 v[208:211], v158 offset:3072
	ds_read_b128 v[212:215], v158 offset:4096
	ds_read_b128 v[216:219], v158 offset:5120
	ds_read_b128 v[220:223], v158 offset:6144
	ds_read_b128 v[224:227], v158 offset:7168
	s_waitcnt vmcnt(24)
	s_waitcnt lgkmcnt(0)
	s_barrier
	v_mfma_f32_16x16x32_bf16 v[126:129], v[142:145], v[196:199], 0
	v_mfma_f32_16x16x32_bf16 v[126:129], v[168:171], v[200:203], v[126:129]
	v_mfma_f32_16x16x32_bf16 v[122:125], v[176:179], v[200:203], 0
	v_mfma_f32_16x16x32_bf16 v[122:125], v[172:175], v[196:199], v[122:125]
	v_mfma_f32_16x16x32_bf16 v[106:109], v[172:175], v[204:207], 0
	v_mfma_f32_16x16x32_bf16 v[106:109], v[176:179], v[208:211], v[106:109]
	v_mfma_f32_16x16x32_bf16 v[110:113], v[168:171], v[208:211], 0
	v_mfma_f32_16x16x32_bf16 v[110:113], v[142:145], v[204:207], v[110:113]
	v_mfma_f32_16x16x32_bf16 v[94:97], v[142:145], v[212:215], 0
	v_mfma_f32_16x16x32_bf16 v[94:97], v[168:171], v[216:219], v[94:97]
	v_mfma_f32_16x16x32_bf16 v[90:93], v[176:179], v[216:219], 0
	v_mfma_f32_16x16x32_bf16 v[90:93], v[172:175], v[212:215], v[90:93]
	v_mfma_f32_16x16x32_bf16 v[74:77], v[172:175], v[220:223], 0
	v_mfma_f32_16x16x32_bf16 v[74:77], v[176:179], v[224:227], v[74:77]
	v_mfma_f32_16x16x32_bf16 v[78:81], v[168:171], v[224:227], 0
	v_mfma_f32_16x16x32_bf16 v[78:81], v[142:145], v[220:223], v[78:81]
	v_mfma_f32_16x16x32_bf16 v[70:73], v[180:183], v[220:223], 0
	v_mfma_f32_16x16x32_bf16 v[70:73], v[184:187], v[224:227], v[70:73]
	v_mfma_f32_16x16x32_bf16 v[66:69], v[192:195], v[224:227], 0
	v_mfma_f32_16x16x32_bf16 v[66:69], v[188:191], v[220:223], v[66:69]
	v_mfma_f32_16x16x32_bf16 v[82:85], v[188:191], v[212:215], 0
	v_mfma_f32_16x16x32_bf16 v[82:85], v[192:195], v[216:219], v[82:85]
	v_mfma_f32_16x16x32_bf16 v[86:89], v[184:187], v[216:219], 0
	v_mfma_f32_16x16x32_bf16 v[86:89], v[180:183], v[212:215], v[86:89]
	v_mfma_f32_16x16x32_bf16 v[102:105], v[180:183], v[204:207], 0
	v_mfma_f32_16x16x32_bf16 v[102:105], v[184:187], v[208:211], v[102:105]
	v_mfma_f32_16x16x32_bf16 v[98:101], v[192:195], v[208:211], 0
	v_mfma_f32_16x16x32_bf16 v[98:101], v[188:191], v[204:207], v[98:101]
	v_mfma_f32_16x16x32_bf16 v[114:117], v[188:191], v[196:199], 0
	v_mfma_f32_16x16x32_bf16 v[114:117], v[192:195], v[200:203], v[114:117]
	v_mfma_f32_16x16x32_bf16 v[118:121], v[184:187], v[200:203], 0
	v_mfma_f32_16x16x32_bf16 v[118:121], v[180:183], v[196:199], v[118:121]
	s_barrier
	s_mov_b32 m0, s48
	s_add_u32 s64, s30, 0x2b0000
	global_load_lds_dwordx4 v132, s[30:31]
	s_mov_b32 m0, s49
	s_addc_u32 s65, s31, 0
	global_load_lds_dwordx4 v136, s[30:31]
	s_mov_b32 m0, s50
	ds_read_b128 v[196:199], v158 offset:16384
	global_load_lds_dwordx4 v132, s[64:65]
	s_mov_b32 m0, s51
	ds_read_b128 v[200:203], v158 offset:17408
	global_load_lds_dwordx4 v136, s[64:65]
	ds_read_b128 v[204:207], v158 offset:18432
	ds_read_b128 v[208:211], v158 offset:19456
	ds_read_b128 v[212:215], v158 offset:20480
	ds_read_b128 v[216:219], v158 offset:21504
	ds_read_b128 v[220:223], v158 offset:22528
	ds_read_b128 v[224:227], v158 offset:23552
	s_waitcnt vmcnt(6)
	s_waitcnt lgkmcnt(0)
	s_barrier
	v_mfma_f32_16x16x32_bf16 v[62:65], v[142:145], v[196:199], 0
	v_mfma_f32_16x16x32_bf16 v[62:65], v[168:171], v[200:203], v[62:65]
	v_mfma_f32_16x16x32_bf16 v[58:61], v[176:179], v[200:203], 0
	v_mfma_f32_16x16x32_bf16 v[58:61], v[172:175], v[196:199], v[58:61]
	v_mfma_f32_16x16x32_bf16 v[42:45], v[172:175], v[204:207], 0
	v_mfma_f32_16x16x32_bf16 v[42:45], v[176:179], v[208:211], v[42:45]
	v_mfma_f32_16x16x32_bf16 v[46:49], v[168:171], v[208:211], 0
	v_mfma_f32_16x16x32_bf16 v[46:49], v[142:145], v[204:207], v[46:49]
	v_mfma_f32_16x16x32_bf16 v[30:33], v[142:145], v[212:215], 0
	v_mfma_f32_16x16x32_bf16 v[30:33], v[168:171], v[216:219], v[30:33]
	v_mfma_f32_16x16x32_bf16 v[26:29], v[176:179], v[216:219], 0
	v_mfma_f32_16x16x32_bf16 v[26:29], v[172:175], v[212:215], v[26:29]
	v_mfma_f32_16x16x32_bf16 v[10:13], v[172:175], v[220:223], 0
	v_mfma_f32_16x16x32_bf16 v[10:13], v[176:179], v[224:227], v[10:13]
	v_mfma_f32_16x16x32_bf16 v[14:17], v[168:171], v[224:227], 0
	v_mfma_f32_16x16x32_bf16 v[14:17], v[142:145], v[220:223], v[14:17]
	v_mfma_f32_16x16x32_bf16 v[6:9], v[180:183], v[220:223], 0
	v_mfma_f32_16x16x32_bf16 v[6:9], v[184:187], v[224:227], v[6:9]
	v_mfma_f32_16x16x32_bf16 v[2:5], v[192:195], v[224:227], 0
	v_mfma_f32_16x16x32_bf16 v[2:5], v[188:191], v[220:223], v[2:5]
	v_mfma_f32_16x16x32_bf16 v[18:21], v[188:191], v[212:215], 0
	v_mfma_f32_16x16x32_bf16 v[18:21], v[192:195], v[216:219], v[18:21]
	v_mfma_f32_16x16x32_bf16 v[22:25], v[184:187], v[216:219], 0
	v_mfma_f32_16x16x32_bf16 v[22:25], v[180:183], v[212:215], v[22:25]
	v_mfma_f32_16x16x32_bf16 v[38:41], v[180:183], v[204:207], 0
	v_mfma_f32_16x16x32_bf16 v[38:41], v[184:187], v[208:211], v[38:41]
	v_mfma_f32_16x16x32_bf16 v[34:37], v[192:195], v[208:211], 0
	v_mfma_f32_16x16x32_bf16 v[34:37], v[188:191], v[204:207], v[34:37]
	v_mfma_f32_16x16x32_bf16 v[50:53], v[188:191], v[196:199], 0
	v_mfma_f32_16x16x32_bf16 v[50:53], v[192:195], v[200:203], v[50:53]
	v_mfma_f32_16x16x32_bf16 v[54:57], v[184:187], v[200:203], 0
	v_mfma_f32_16x16x32_bf16 v[54:57], v[180:183], v[196:199], v[54:57]
	s_barrier
	s_mov_b32 m0, s39
	ds_read_b128 v[142:145], v159
	global_load_lds_dwordx4 v130, s[34:35]
	s_mov_b32 m0, s40
	ds_read_b128 v[168:171], v159 offset:1024
	global_load_lds_dwordx4 v134, s[34:35]
	s_add_u32 s34, s34, 0x2b0000
	s_addc_u32 s35, s35, 0
	s_mov_b32 m0, s41
	ds_read_b128 v[172:175], v159 offset:2048
	global_load_lds_dwordx4 v130, s[34:35]
	s_mov_b32 m0, s42
	ds_read_b128 v[176:179], v159 offset:3072
	global_load_lds_dwordx4 v134, s[34:35]
	ds_read_b128 v[180:183], v160
	ds_read_b128 v[184:187], v160 offset:1024
	ds_read_b128 v[188:191], v160 offset:2048
	ds_read_b128 v[192:195], v160 offset:3072
	ds_read_b128 v[196:199], v158 offset:32768
	ds_read_b128 v[200:203], v158 offset:33792
	ds_read_b128 v[204:207], v158 offset:34816
	ds_read_b128 v[208:211], v158 offset:35840
	ds_read_b128 v[212:215], v158 offset:36864
	ds_read_b128 v[216:219], v158 offset:37888
	ds_read_b128 v[220:223], v158 offset:38912
	ds_read_b128 v[224:227], v158 offset:39936
	s_waitcnt vmcnt(8)
	s_waitcnt lgkmcnt(0)
	s_barrier
	v_mfma_f32_16x16x32_bf16 v[126:129], v[142:145], v[196:199], v[126:129]
	v_mfma_f32_16x16x32_bf16 v[126:129], v[168:171], v[200:203], v[126:129]
	v_mfma_f32_16x16x32_bf16 v[122:125], v[176:179], v[200:203], v[122:125]
	v_mfma_f32_16x16x32_bf16 v[122:125], v[172:175], v[196:199], v[122:125]
	v_mfma_f32_16x16x32_bf16 v[106:109], v[172:175], v[204:207], v[106:109]
	v_mfma_f32_16x16x32_bf16 v[106:109], v[176:179], v[208:211], v[106:109]
	v_mfma_f32_16x16x32_bf16 v[110:113], v[168:171], v[208:211], v[110:113]
	v_mfma_f32_16x16x32_bf16 v[110:113], v[142:145], v[204:207], v[110:113]
	v_mfma_f32_16x16x32_bf16 v[94:97], v[142:145], v[212:215], v[94:97]
	v_mfma_f32_16x16x32_bf16 v[94:97], v[168:171], v[216:219], v[94:97]
	v_mfma_f32_16x16x32_bf16 v[90:93], v[176:179], v[216:219], v[90:93]
	v_mfma_f32_16x16x32_bf16 v[90:93], v[172:175], v[212:215], v[90:93]
	v_mfma_f32_16x16x32_bf16 v[74:77], v[172:175], v[220:223], v[74:77]
	v_mfma_f32_16x16x32_bf16 v[74:77], v[176:179], v[224:227], v[74:77]
	v_mfma_f32_16x16x32_bf16 v[78:81], v[168:171], v[224:227], v[78:81]
	v_mfma_f32_16x16x32_bf16 v[78:81], v[142:145], v[220:223], v[78:81]
	v_mfma_f32_16x16x32_bf16 v[70:73], v[180:183], v[220:223], v[70:73]
	v_mfma_f32_16x16x32_bf16 v[70:73], v[184:187], v[224:227], v[70:73]
	v_mfma_f32_16x16x32_bf16 v[66:69], v[192:195], v[224:227], v[66:69]
	v_mfma_f32_16x16x32_bf16 v[66:69], v[188:191], v[220:223], v[66:69]
	v_mfma_f32_16x16x32_bf16 v[82:85], v[188:191], v[212:215], v[82:85]
	v_mfma_f32_16x16x32_bf16 v[82:85], v[192:195], v[216:219], v[82:85]
	v_mfma_f32_16x16x32_bf16 v[86:89], v[184:187], v[216:219], v[86:89]
	v_mfma_f32_16x16x32_bf16 v[86:89], v[180:183], v[212:215], v[86:89]
	v_mfma_f32_16x16x32_bf16 v[102:105], v[180:183], v[204:207], v[102:105]
	v_mfma_f32_16x16x32_bf16 v[102:105], v[184:187], v[208:211], v[102:105]
	v_mfma_f32_16x16x32_bf16 v[98:101], v[192:195], v[208:211], v[98:101]
	v_mfma_f32_16x16x32_bf16 v[98:101], v[188:191], v[204:207], v[98:101]
	v_mfma_f32_16x16x32_bf16 v[114:117], v[188:191], v[196:199], v[114:117]
	v_mfma_f32_16x16x32_bf16 v[114:117], v[192:195], v[200:203], v[114:117]
	v_mfma_f32_16x16x32_bf16 v[118:121], v[184:187], v[200:203], v[118:121]
	v_mfma_f32_16x16x32_bf16 v[118:121], v[180:183], v[196:199], v[118:121]
	s_barrier
	s_mov_b32 m0, s52
	s_add_u32 s30, s30, 0x80
	s_addc_u32 s31, s31, 0
	global_load_lds_dwordx4 v132, s[30:31]
	s_mov_b32 m0, s53
	ds_read_b128 v[196:199], v158 offset:49152
	global_load_lds_dwordx4 v136, s[30:31]
	s_mov_b32 m0, s54
	s_add_u32 s30, s30, 0x2b0000
	s_addc_u32 s31, s31, 0
	global_load_lds_dwordx4 v132, s[30:31]
	s_mov_b32 m0, s55
	ds_read_b128 v[200:203], v158 offset:50176
	global_load_lds_dwordx4 v136, s[30:31]
	ds_read_b128 v[204:207], v158 offset:51200
	ds_read_b128 v[208:211], v158 offset:52224
	ds_read_b128 v[212:215], v158 offset:53248
	ds_read_b128 v[216:219], v158 offset:54272
	ds_read_b128 v[220:223], v158 offset:55296
	ds_read_b128 v[224:227], v158 offset:56320
	s_waitcnt vmcnt(6)
	s_waitcnt lgkmcnt(0)
	s_barrier
	v_mfma_f32_16x16x32_bf16 v[62:65], v[142:145], v[196:199], v[62:65]
	v_mfma_f32_16x16x32_bf16 v[62:65], v[168:171], v[200:203], v[62:65]
	v_mfma_f32_16x16x32_bf16 v[58:61], v[176:179], v[200:203], v[58:61]
	v_mfma_f32_16x16x32_bf16 v[58:61], v[172:175], v[196:199], v[58:61]
	v_mfma_f32_16x16x32_bf16 v[42:45], v[172:175], v[204:207], v[42:45]
	v_mfma_f32_16x16x32_bf16 v[42:45], v[176:179], v[208:211], v[42:45]
	v_mfma_f32_16x16x32_bf16 v[46:49], v[168:171], v[208:211], v[46:49]
	v_mfma_f32_16x16x32_bf16 v[46:49], v[142:145], v[204:207], v[46:49]
	v_mfma_f32_16x16x32_bf16 v[30:33], v[142:145], v[212:215], v[30:33]
	v_mfma_f32_16x16x32_bf16 v[30:33], v[168:171], v[216:219], v[30:33]
	v_mfma_f32_16x16x32_bf16 v[26:29], v[176:179], v[216:219], v[26:29]
	v_mfma_f32_16x16x32_bf16 v[26:29], v[172:175], v[212:215], v[26:29]
	v_mfma_f32_16x16x32_bf16 v[10:13], v[172:175], v[220:223], v[10:13]
	v_mfma_f32_16x16x32_bf16 v[10:13], v[176:179], v[224:227], v[10:13]
	v_mfma_f32_16x16x32_bf16 v[14:17], v[168:171], v[224:227], v[14:17]
	v_mfma_f32_16x16x32_bf16 v[14:17], v[142:145], v[220:223], v[14:17]
	v_mfma_f32_16x16x32_bf16 v[6:9], v[180:183], v[220:223], v[6:9]
	v_mfma_f32_16x16x32_bf16 v[6:9], v[184:187], v[224:227], v[6:9]
	v_mfma_f32_16x16x32_bf16 v[2:5], v[192:195], v[224:227], v[2:5]
	v_mfma_f32_16x16x32_bf16 v[2:5], v[188:191], v[220:223], v[2:5]
	v_mfma_f32_16x16x32_bf16 v[18:21], v[188:191], v[212:215], v[18:21]
	v_mfma_f32_16x16x32_bf16 v[18:21], v[192:195], v[216:219], v[18:21]
	v_mfma_f32_16x16x32_bf16 v[22:25], v[184:187], v[216:219], v[22:25]
	v_mfma_f32_16x16x32_bf16 v[22:25], v[180:183], v[212:215], v[22:25]
	v_mfma_f32_16x16x32_bf16 v[38:41], v[180:183], v[204:207], v[38:41]
	v_mfma_f32_16x16x32_bf16 v[38:41], v[184:187], v[208:211], v[38:41]
	v_mfma_f32_16x16x32_bf16 v[34:37], v[192:195], v[208:211], v[34:37]
	v_mfma_f32_16x16x32_bf16 v[34:37], v[188:191], v[204:207], v[34:37]
	v_mfma_f32_16x16x32_bf16 v[50:53], v[188:191], v[196:199], v[50:53]
	v_mfma_f32_16x16x32_bf16 v[50:53], v[192:195], v[200:203], v[50:53]
	v_mfma_f32_16x16x32_bf16 v[54:57], v[184:187], v[200:203], v[54:57]
	v_mfma_f32_16x16x32_bf16 v[54:57], v[180:183], v[196:199], v[54:57]
	s_barrier
	s_add_i32 s62, s62, 2
	s_add_u32 s28, s28, 0x100
	s_addc_u32 s29, s29, 0
	s_add_u32 s60, s60, 0x100
	s_addc_u32 s61, s61, 0
